# v14 + full compute-segment cleanup (no-op waits removed, setprio 0 behind / setprio 1 ahead of barriers, mid yield removed)
# speedup vs baseline: 1.0070x; 1.0045x over previous
.LBB0_121:
	ds_read_b128 v[164:167], v131
	ds_read_b128 v[168:171], v131 offset:1024
	ds_read_b128 v[172:175], v131 offset:2048
	ds_read_b128 v[176:179], v131 offset:3072
	ds_read_b128 v[180:183], v160
	ds_read_b128 v[184:187], v160 offset:1024
	ds_read_b128 v[188:191], v160 offset:2048
	ds_read_b128 v[192:195], v160 offset:3072
	s_add_i32 s55, s52, 0xfffc0080
	s_cmp_eq_u32 s54, 12
	s_cselect_b32 s57, s16, s55
	s_cselect_b32 s56, s17, s53
	s_or_b32 s55, s57, 0x80
	s_mov_b32 m0, s40
	s_nop 0
	buffer_load_dwordx4 v156, s[12:15], s52 offen lds
	s_nop 0
	s_mov_b32 m0, s41
	s_nop 0
	buffer_load_dwordx4 v157, s[12:15], s52 offen lds
	ds_read_b128 v[196:199], v161
	ds_read_b128 v[200:203], v161 offset:1024
	ds_read_b128 v[204:207], v161 offset:2048
	ds_read_b128 v[208:211], v161 offset:3072
	ds_read_b128 v[212:215], v161 offset:4096
	ds_read_b128 v[216:219], v161 offset:5120
	ds_read_b128 v[220:223], v161 offset:6144
	ds_read_b128 v[224:227], v161 offset:7168
	s_waitcnt vmcnt(8)
	s_waitcnt lgkmcnt(0)
	s_setprio 1
	s_barrier
	v_mfma_f32_16x16x32_bf16 v[126:129], v[164:167], v[196:199], v[126:129]
	v_mfma_f32_16x16x32_bf16 v[122:125], v[172:175], v[196:199], v[122:125]
	v_mfma_f32_16x16x32_bf16 v[118:121], v[164:167], v[204:207], v[118:121]
	v_mfma_f32_16x16x32_bf16 v[110:113], v[172:175], v[204:207], v[110:113]
	v_mfma_f32_16x16x32_bf16 v[102:105], v[164:167], v[212:215], v[102:105]
	v_mfma_f32_16x16x32_bf16 v[94:97], v[172:175], v[212:215], v[94:97]
	v_mfma_f32_16x16x32_bf16 v[86:89], v[164:167], v[220:223], v[86:89]
	v_mfma_f32_16x16x32_bf16 v[78:81], v[172:175], v[220:223], v[78:81]
	v_mfma_f32_16x16x32_bf16 v[126:129], v[168:171], v[200:203], v[126:129]
	v_mfma_f32_16x16x32_bf16 v[122:125], v[176:179], v[200:203], v[122:125]
	v_mfma_f32_16x16x32_bf16 v[118:121], v[168:171], v[208:211], v[118:121]
	v_mfma_f32_16x16x32_bf16 v[110:113], v[176:179], v[208:211], v[110:113]
	v_mfma_f32_16x16x32_bf16 v[102:105], v[168:171], v[216:219], v[102:105]
	v_mfma_f32_16x16x32_bf16 v[94:97], v[176:179], v[216:219], v[94:97]
	v_mfma_f32_16x16x32_bf16 v[86:89], v[168:171], v[224:227], v[86:89]
	v_mfma_f32_16x16x32_bf16 v[78:81], v[176:179], v[224:227], v[78:81]
	v_mfma_f32_16x16x32_bf16 v[114:117], v[180:183], v[196:199], v[114:117]
	v_mfma_f32_16x16x32_bf16 v[106:109], v[188:191], v[196:199], v[106:109]
	v_mfma_f32_16x16x32_bf16 v[98:101], v[180:183], v[204:207], v[98:101]
	v_mfma_f32_16x16x32_bf16 v[90:93], v[188:191], v[204:207], v[90:93]
	v_mfma_f32_16x16x32_bf16 v[82:85], v[180:183], v[212:215], v[82:85]
	v_mfma_f32_16x16x32_bf16 v[74:77], v[188:191], v[212:215], v[74:77]
	v_mfma_f32_16x16x32_bf16 v[70:73], v[180:183], v[220:223], v[70:73]
	v_mfma_f32_16x16x32_bf16 v[66:69], v[188:191], v[220:223], v[66:69]
	v_mfma_f32_16x16x32_bf16 v[114:117], v[184:187], v[200:203], v[114:117]
	v_mfma_f32_16x16x32_bf16 v[106:109], v[192:195], v[200:203], v[106:109]
	v_mfma_f32_16x16x32_bf16 v[98:101], v[184:187], v[208:211], v[98:101]
	v_mfma_f32_16x16x32_bf16 v[90:93], v[192:195], v[208:211], v[90:93]
	v_mfma_f32_16x16x32_bf16 v[82:85], v[184:187], v[216:219], v[82:85]
	v_mfma_f32_16x16x32_bf16 v[74:77], v[192:195], v[216:219], v[74:77]
	v_mfma_f32_16x16x32_bf16 v[70:73], v[184:187], v[224:227], v[70:73]
	v_mfma_f32_16x16x32_bf16 v[66:69], v[192:195], v[224:227], v[66:69]
	s_barrier
	s_setprio 0
	ds_read_b128 v[196:199], v161 offset:16384
	ds_read_b128 v[200:203], v161 offset:17408
	s_mov_b32 m0, s22
	s_nop 0
	buffer_load_dwordx4 v154, s[8:11], s56 offen lds
	ds_read_b128 v[204:207], v161 offset:18432
	ds_read_b128 v[208:211], v161 offset:19456
	s_add_i32 s58, s56, 0x40000
	s_mov_b32 m0, s23
	s_nop 0
	buffer_load_dwordx4 v155, s[8:11], s56 offen lds
	ds_read_b128 v[212:215], v161 offset:20480
	ds_read_b128 v[216:219], v161 offset:21504
	s_nop 0
	s_mov_b32 m0, s24
	s_nop 0
	buffer_load_dwordx4 v154, s[8:11], s58 offen lds
	ds_read_b128 v[220:223], v161 offset:22528
	ds_read_b128 v[224:227], v161 offset:23552
	s_nop 0
	s_mov_b32 m0, s25
	s_nop 0
	buffer_load_dwordx4 v155, s[8:11], s58 offen lds
	s_nop 0
	s_mov_b32 m0, s21
	s_nop 0
	buffer_load_dwordx4 v156, s[12:15], s57 offen lds
	s_nop 0
	s_mov_b32 m0, s27
	s_nop 0
	buffer_load_dwordx4 v157, s[12:15], s57 offen lds
	s_waitcnt vmcnt(8)
	s_waitcnt lgkmcnt(0)
	s_setprio 1
	s_barrier
	v_mfma_f32_16x16x32_bf16 v[62:65], v[164:167], v[196:199], v[62:65]
	v_mfma_f32_16x16x32_bf16 v[58:61], v[172:175], v[196:199], v[58:61]
	v_mfma_f32_16x16x32_bf16 v[54:57], v[164:167], v[204:207], v[54:57]
	v_mfma_f32_16x16x32_bf16 v[46:49], v[172:175], v[204:207], v[46:49]
	v_mfma_f32_16x16x32_bf16 v[38:41], v[164:167], v[212:215], v[38:41]
	v_mfma_f32_16x16x32_bf16 v[30:33], v[172:175], v[212:215], v[30:33]
	v_mfma_f32_16x16x32_bf16 v[22:25], v[164:167], v[220:223], v[22:25]
	v_mfma_f32_16x16x32_bf16 v[14:17], v[172:175], v[220:223], v[14:17]
	v_mfma_f32_16x16x32_bf16 v[62:65], v[168:171], v[200:203], v[62:65]
	v_mfma_f32_16x16x32_bf16 v[58:61], v[176:179], v[200:203], v[58:61]
	v_mfma_f32_16x16x32_bf16 v[54:57], v[168:171], v[208:211], v[54:57]
	v_mfma_f32_16x16x32_bf16 v[46:49], v[176:179], v[208:211], v[46:49]
	v_mfma_f32_16x16x32_bf16 v[38:41], v[168:171], v[216:219], v[38:41]
	v_mfma_f32_16x16x32_bf16 v[30:33], v[176:179], v[216:219], v[30:33]
	v_mfma_f32_16x16x32_bf16 v[22:25], v[168:171], v[224:227], v[22:25]
	v_mfma_f32_16x16x32_bf16 v[14:17], v[176:179], v[224:227], v[14:17]
	v_mfma_f32_16x16x32_bf16 v[50:53], v[180:183], v[196:199], v[50:53]
	v_mfma_f32_16x16x32_bf16 v[42:45], v[188:191], v[196:199], v[42:45]
	v_mfma_f32_16x16x32_bf16 v[34:37], v[180:183], v[204:207], v[34:37]
	v_mfma_f32_16x16x32_bf16 v[26:29], v[188:191], v[204:207], v[26:29]
	v_mfma_f32_16x16x32_bf16 v[18:21], v[180:183], v[212:215], v[18:21]
	v_mfma_f32_16x16x32_bf16 v[10:13], v[188:191], v[212:215], v[10:13]
	v_mfma_f32_16x16x32_bf16 v[6:9], v[180:183], v[220:223], v[6:9]
	v_mfma_f32_16x16x32_bf16 v[2:5], v[188:191], v[220:223], v[2:5]
	v_mfma_f32_16x16x32_bf16 v[50:53], v[184:187], v[200:203], v[50:53]
	v_mfma_f32_16x16x32_bf16 v[42:45], v[192:195], v[200:203], v[42:45]
	v_mfma_f32_16x16x32_bf16 v[34:37], v[184:187], v[208:211], v[34:37]
	v_mfma_f32_16x16x32_bf16 v[26:29], v[192:195], v[208:211], v[26:29]
	v_mfma_f32_16x16x32_bf16 v[18:21], v[184:187], v[216:219], v[18:21]
	v_mfma_f32_16x16x32_bf16 v[10:13], v[192:195], v[216:219], v[10:13]
	v_mfma_f32_16x16x32_bf16 v[6:9], v[184:187], v[224:227], v[6:9]
	v_mfma_f32_16x16x32_bf16 v[2:5], v[192:195], v[224:227], v[2:5]
	s_barrier
	s_setprio 0
	ds_read_b128 v[164:167], v162
	ds_read_b128 v[168:171], v162 offset:1024
	ds_read_b128 v[172:175], v162 offset:2048
	ds_read_b128 v[176:179], v162 offset:3072
	ds_read_b128 v[180:183], v163
	ds_read_b128 v[184:187], v163 offset:1024
	ds_read_b128 v[188:191], v163 offset:2048
	ds_read_b128 v[192:195], v163 offset:3072
	s_add_i32 s57, s57, 0x40000
	s_mov_b32 m0, s28
	s_nop 0
	buffer_load_dwordx4 v156, s[12:15], s57 offen lds
	s_nop 0
	s_mov_b32 m0, s30
	s_nop 0
	buffer_load_dwordx4 v157, s[12:15], s57 offen lds
	ds_read_b128 v[196:199], v161 offset:32768
	ds_read_b128 v[200:203], v161 offset:33792
	ds_read_b128 v[204:207], v161 offset:34816
	ds_read_b128 v[208:211], v161 offset:35840
	ds_read_b128 v[212:215], v161 offset:36864
	ds_read_b128 v[216:219], v161 offset:37888
	ds_read_b128 v[220:223], v161 offset:38912
	ds_read_b128 v[224:227], v161 offset:39936
	s_waitcnt vmcnt(8)
	s_waitcnt lgkmcnt(0)
	s_setprio 1
	s_barrier
	v_mfma_f32_16x16x32_bf16 v[126:129], v[164:167], v[196:199], v[126:129]
	v_mfma_f32_16x16x32_bf16 v[122:125], v[172:175], v[196:199], v[122:125]
	v_mfma_f32_16x16x32_bf16 v[118:121], v[164:167], v[204:207], v[118:121]
	v_mfma_f32_16x16x32_bf16 v[110:113], v[172:175], v[204:207], v[110:113]
	v_mfma_f32_16x16x32_bf16 v[102:105], v[164:167], v[212:215], v[102:105]
	v_mfma_f32_16x16x32_bf16 v[94:97], v[172:175], v[212:215], v[94:97]
	v_mfma_f32_16x16x32_bf16 v[86:89], v[164:167], v[220:223], v[86:89]
	v_mfma_f32_16x16x32_bf16 v[78:81], v[172:175], v[220:223], v[78:81]
	v_mfma_f32_16x16x32_bf16 v[126:129], v[168:171], v[200:203], v[126:129]
	v_mfma_f32_16x16x32_bf16 v[122:125], v[176:179], v[200:203], v[122:125]
	v_mfma_f32_16x16x32_bf16 v[118:121], v[168:171], v[208:211], v[118:121]
	v_mfma_f32_16x16x32_bf16 v[110:113], v[176:179], v[208:211], v[110:113]
	v_mfma_f32_16x16x32_bf16 v[102:105], v[168:171], v[216:219], v[102:105]
	v_mfma_f32_16x16x32_bf16 v[94:97], v[176:179], v[216:219], v[94:97]
	v_mfma_f32_16x16x32_bf16 v[86:89], v[168:171], v[224:227], v[86:89]
	v_mfma_f32_16x16x32_bf16 v[78:81], v[176:179], v[224:227], v[78:81]
	v_mfma_f32_16x16x32_bf16 v[114:117], v[180:183], v[196:199], v[114:117]
	v_mfma_f32_16x16x32_bf16 v[106:109], v[188:191], v[196:199], v[106:109]
	v_mfma_f32_16x16x32_bf16 v[98:101], v[180:183], v[204:207], v[98:101]
	v_mfma_f32_16x16x32_bf16 v[90:93], v[188:191], v[204:207], v[90:93]
	v_mfma_f32_16x16x32_bf16 v[82:85], v[180:183], v[212:215], v[82:85]
	v_mfma_f32_16x16x32_bf16 v[74:77], v[188:191], v[212:215], v[74:77]
	v_mfma_f32_16x16x32_bf16 v[70:73], v[180:183], v[220:223], v[70:73]
	v_mfma_f32_16x16x32_bf16 v[66:69], v[188:191], v[220:223], v[66:69]
	v_mfma_f32_16x16x32_bf16 v[114:117], v[184:187], v[200:203], v[114:117]
	v_mfma_f32_16x16x32_bf16 v[106:109], v[192:195], v[200:203], v[106:109]
	v_mfma_f32_16x16x32_bf16 v[98:101], v[184:187], v[208:211], v[98:101]
	v_mfma_f32_16x16x32_bf16 v[90:93], v[192:195], v[208:211], v[90:93]
	v_mfma_f32_16x16x32_bf16 v[82:85], v[184:187], v[216:219], v[82:85]
	v_mfma_f32_16x16x32_bf16 v[74:77], v[192:195], v[216:219], v[74:77]
	v_mfma_f32_16x16x32_bf16 v[70:73], v[184:187], v[224:227], v[70:73]
	v_mfma_f32_16x16x32_bf16 v[66:69], v[192:195], v[224:227], v[66:69]
	s_barrier
	s_setprio 0
	ds_read_b128 v[196:199], v161 offset:49152
	ds_read_b128 v[200:203], v161 offset:50176
	s_or_b32 s57, s56, 0x80
	s_mov_b32 m0, s34
	s_nop 0
	buffer_load_dwordx4 v154, s[8:11], s57 offen lds
	ds_read_b128 v[204:207], v161 offset:51200
	ds_read_b128 v[208:211], v161 offset:52224
	s_add_i32 s56, s56, 0x40080
	s_mov_b32 m0, s35
	s_nop 0
	buffer_load_dwordx4 v155, s[8:11], s57 offen lds
	ds_read_b128 v[212:215], v161 offset:53248
	ds_read_b128 v[216:219], v161 offset:54272
	s_nop 0
	s_mov_b32 m0, s38
	s_nop 0
	buffer_load_dwordx4 v154, s[8:11], s56 offen lds
	ds_read_b128 v[220:223], v161 offset:55296
	ds_read_b128 v[224:227], v161 offset:56320
	s_nop 0
	s_mov_b32 m0, s39
	s_nop 0
	buffer_load_dwordx4 v155, s[8:11], s56 offen lds
	s_nop 0
	s_mov_b32 m0, s36
	s_nop 0
	buffer_load_dwordx4 v156, s[12:15], s55 offen lds
	s_nop 0
	s_mov_b32 m0, s37
	s_nop 0
	buffer_load_dwordx4 v157, s[12:15], s55 offen lds
	s_waitcnt vmcnt(8)
	s_waitcnt lgkmcnt(0)
	s_setprio 1
	s_barrier
	v_mfma_f32_16x16x32_bf16 v[62:65], v[164:167], v[196:199], v[62:65]
	v_mfma_f32_16x16x32_bf16 v[58:61], v[172:175], v[196:199], v[58:61]
	v_mfma_f32_16x16x32_bf16 v[54:57], v[164:167], v[204:207], v[54:57]
	v_mfma_f32_16x16x32_bf16 v[46:49], v[172:175], v[204:207], v[46:49]
	v_mfma_f32_16x16x32_bf16 v[38:41], v[164:167], v[212:215], v[38:41]
	v_mfma_f32_16x16x32_bf16 v[30:33], v[172:175], v[212:215], v[30:33]
	v_mfma_f32_16x16x32_bf16 v[22:25], v[164:167], v[220:223], v[22:25]
	v_mfma_f32_16x16x32_bf16 v[14:17], v[172:175], v[220:223], v[14:17]
	v_mfma_f32_16x16x32_bf16 v[62:65], v[168:171], v[200:203], v[62:65]
	v_mfma_f32_16x16x32_bf16 v[58:61], v[176:179], v[200:203], v[58:61]
	v_mfma_f32_16x16x32_bf16 v[54:57], v[168:171], v[208:211], v[54:57]
	v_mfma_f32_16x16x32_bf16 v[46:49], v[176:179], v[208:211], v[46:49]
	v_mfma_f32_16x16x32_bf16 v[38:41], v[168:171], v[216:219], v[38:41]
	v_mfma_f32_16x16x32_bf16 v[30:33], v[176:179], v[216:219], v[30:33]
	v_mfma_f32_16x16x32_bf16 v[22:25], v[168:171], v[224:227], v[22:25]
	v_mfma_f32_16x16x32_bf16 v[14:17], v[176:179], v[224:227], v[14:17]
	v_mfma_f32_16x16x32_bf16 v[50:53], v[180:183], v[196:199], v[50:53]
	v_mfma_f32_16x16x32_bf16 v[42:45], v[188:191], v[196:199], v[42:45]
	v_mfma_f32_16x16x32_bf16 v[34:37], v[180:183], v[204:207], v[34:37]
	v_mfma_f32_16x16x32_bf16 v[26:29], v[188:191], v[204:207], v[26:29]
	v_mfma_f32_16x16x32_bf16 v[18:21], v[180:183], v[212:215], v[18:21]
	v_mfma_f32_16x16x32_bf16 v[10:13], v[188:191], v[212:215], v[10:13]
	v_mfma_f32_16x16x32_bf16 v[6:9], v[180:183], v[220:223], v[6:9]
	v_mfma_f32_16x16x32_bf16 v[2:5], v[188:191], v[220:223], v[2:5]
	v_mfma_f32_16x16x32_bf16 v[50:53], v[184:187], v[200:203], v[50:53]
	v_mfma_f32_16x16x32_bf16 v[42:45], v[192:195], v[200:203], v[42:45]
	v_mfma_f32_16x16x32_bf16 v[34:37], v[184:187], v[208:211], v[34:37]
	v_mfma_f32_16x16x32_bf16 v[26:29], v[192:195], v[208:211], v[26:29]
	v_mfma_f32_16x16x32_bf16 v[18:21], v[184:187], v[216:219], v[18:21]
	v_mfma_f32_16x16x32_bf16 v[10:13], v[192:195], v[216:219], v[10:13]
	v_mfma_f32_16x16x32_bf16 v[6:9], v[184:187], v[224:227], v[6:9]
	v_mfma_f32_16x16x32_bf16 v[2:5], v[192:195], v[224:227], v[2:5]
	s_barrier
	s_setprio 0
	s_add_i32 s54, s54, 2
	s_addk_i32 s52, 0x100
	s_addk_i32 s53, 0x100
	s_cmp_gt_u32 s54, 13
	s_cbranch_scc0 .LBB0_121
	s_and_b64 vcc, exec, s[6:7]
	s_cbranch_vccz .LBB0_126
	s_barrier
	s_cmp_gt_i32 s46, 3
	s_mov_b64 s[16:17], -1
	s_cbranch_scc1 .LBB0_127

.LBB0_223:
	v_add_u32_e32 v150, 0x10000, v132
	v_add_u32_e32 v166, 0x14000, v132
	ds_read_b128 v[134:137], v150
	ds_read_b128 v[142:145], v150 offset:1024
	ds_read_b128 v[146:149], v150 offset:2048
	ds_read_b128 v[150:153], v150 offset:3072
	ds_read_b128 v[154:157], v166
	ds_read_b128 v[158:161], v166 offset:1024
	ds_read_b128 v[162:165], v166 offset:2048
	ds_read_b128 v[166:169], v166 offset:3072
	s_add_i32 s63, s39, s60
	s_add_i32 s62, s34, s60
	s_add_i32 s61, s63, 0x800
	s_addk_i32 s62, 0x800
	s_cmp_eq_u32 s60, 0
	s_cselect_b32 s64, s55, s61
	s_cselect_b32 s62, s58, s62
	s_or_b32 s61, s64, 0x80
	s_add_i32 s63, s63, 0x40780
	s_mov_b32 m0, s49
	s_nop 0
	buffer_load_dwordx4 v130, s[12:15], s63 offen lds
	s_nop 0
	s_mov_b32 m0, s50
	s_nop 0
	buffer_load_dwordx4 v131, s[12:15], s63 offen lds
	ds_read_b128 v[170:173], v133
	ds_read_b128 v[174:177], v133 offset:1024
	ds_read_b128 v[178:181], v133 offset:2048
	ds_read_b128 v[182:185], v133 offset:3072
	ds_read_b128 v[186:189], v133 offset:4096
	ds_read_b128 v[190:193], v133 offset:5120
	ds_read_b128 v[194:197], v133 offset:6144
	ds_read_b128 v[198:201], v133 offset:7168
	s_waitcnt vmcnt(8)
	s_waitcnt lgkmcnt(0)
	s_setprio 1
	s_barrier
	v_mfma_f32_16x16x32_bf16 v[138:141], v[134:137], v[170:173], v[138:141]
	v_mfma_f32_16x16x32_bf16 v[126:129], v[146:149], v[170:173], v[126:129]
	v_mfma_f32_16x16x32_bf16 v[110:113], v[134:137], v[178:181], v[110:113]
	v_mfma_f32_16x16x32_bf16 v[106:109], v[146:149], v[178:181], v[106:109]
	v_mfma_f32_16x16x32_bf16 v[94:97], v[134:137], v[186:189], v[94:97]
	v_mfma_f32_16x16x32_bf16 v[90:93], v[146:149], v[186:189], v[90:93]
	v_mfma_f32_16x16x32_bf16 v[78:81], v[134:137], v[194:197], v[78:81]
	v_mfma_f32_16x16x32_bf16 v[74:77], v[146:149], v[194:197], v[74:77]
	v_mfma_f32_16x16x32_bf16 v[138:141], v[142:145], v[174:177], v[138:141]
	v_mfma_f32_16x16x32_bf16 v[126:129], v[150:153], v[174:177], v[126:129]
	v_mfma_f32_16x16x32_bf16 v[110:113], v[142:145], v[182:185], v[110:113]
	v_mfma_f32_16x16x32_bf16 v[106:109], v[150:153], v[182:185], v[106:109]
	v_mfma_f32_16x16x32_bf16 v[94:97], v[142:145], v[190:193], v[94:97]
	v_mfma_f32_16x16x32_bf16 v[90:93], v[150:153], v[190:193], v[90:93]
	v_mfma_f32_16x16x32_bf16 v[78:81], v[142:145], v[198:201], v[78:81]
	v_mfma_f32_16x16x32_bf16 v[74:77], v[150:153], v[198:201], v[74:77]
	v_mfma_f32_16x16x32_bf16 v[118:121], v[154:157], v[170:173], v[118:121]
	v_mfma_f32_16x16x32_bf16 v[114:117], v[162:165], v[170:173], v[114:117]
	v_mfma_f32_16x16x32_bf16 v[102:105], v[154:157], v[178:181], v[102:105]
	v_mfma_f32_16x16x32_bf16 v[98:101], v[162:165], v[178:181], v[98:101]
	v_mfma_f32_16x16x32_bf16 v[86:89], v[154:157], v[186:189], v[86:89]
	v_mfma_f32_16x16x32_bf16 v[82:85], v[162:165], v[186:189], v[82:85]
	v_mfma_f32_16x16x32_bf16 v[70:73], v[154:157], v[194:197], v[70:73]
	v_mfma_f32_16x16x32_bf16 v[66:69], v[162:165], v[194:197], v[66:69]
	v_mfma_f32_16x16x32_bf16 v[118:121], v[158:161], v[174:177], v[118:121]
	v_mfma_f32_16x16x32_bf16 v[114:117], v[166:169], v[174:177], v[114:117]
	v_mfma_f32_16x16x32_bf16 v[102:105], v[158:161], v[182:185], v[102:105]
	v_mfma_f32_16x16x32_bf16 v[98:101], v[166:169], v[182:185], v[98:101]
	v_mfma_f32_16x16x32_bf16 v[86:89], v[158:161], v[190:193], v[86:89]
	v_mfma_f32_16x16x32_bf16 v[82:85], v[166:169], v[190:193], v[82:85]
	v_mfma_f32_16x16x32_bf16 v[70:73], v[158:161], v[198:201], v[70:73]
	v_mfma_f32_16x16x32_bf16 v[66:69], v[166:169], v[198:201], v[66:69]
	s_barrier
	s_setprio 0
	ds_read_b128 v[170:173], v133 offset:16384
	ds_read_b128 v[174:177], v133 offset:17408
	s_mov_b32 m0, s33
	s_nop 0
	buffer_load_dwordx4 v130, s[8:11], s62 offen lds
	ds_read_b128 v[178:181], v133 offset:18432
	ds_read_b128 v[182:185], v133 offset:19456
	s_add_i32 s63, s62, 0x40000
	s_mov_b32 m0, s35
	s_nop 0
	buffer_load_dwordx4 v131, s[8:11], s62 offen lds
	ds_read_b128 v[186:189], v133 offset:20480
	ds_read_b128 v[190:193], v133 offset:21504
	s_nop 0
	s_mov_b32 m0, s36
	s_nop 0
	buffer_load_dwordx4 v130, s[8:11], s63 offen lds
	ds_read_b128 v[194:197], v133 offset:22528
	ds_read_b128 v[198:201], v133 offset:23552
	s_nop 0
	s_mov_b32 m0, s37
	s_nop 0
	buffer_load_dwordx4 v131, s[8:11], s63 offen lds
	s_nop 0
	s_mov_b32 m0, s31
	s_nop 0
	buffer_load_dwordx4 v130, s[12:15], s64 offen lds
	s_nop 0
	s_mov_b32 m0, s40
	s_nop 0
	buffer_load_dwordx4 v131, s[12:15], s64 offen lds
	s_waitcnt vmcnt(8)
	s_waitcnt lgkmcnt(0)
	s_setprio 1
	s_barrier
	v_mfma_f32_16x16x32_bf16 v[62:65], v[134:137], v[170:173], v[62:65]
	v_mfma_f32_16x16x32_bf16 v[58:61], v[146:149], v[170:173], v[58:61]
	v_mfma_f32_16x16x32_bf16 v[46:49], v[134:137], v[178:181], v[46:49]
	v_mfma_f32_16x16x32_bf16 v[42:45], v[146:149], v[178:181], v[42:45]
	v_mfma_f32_16x16x32_bf16 v[30:33], v[134:137], v[186:189], v[30:33]
	v_mfma_f32_16x16x32_bf16 v[26:29], v[146:149], v[186:189], v[26:29]
	v_mfma_f32_16x16x32_bf16 v[14:17], v[134:137], v[194:197], v[14:17]
	v_mfma_f32_16x16x32_bf16 v[10:13], v[146:149], v[194:197], v[10:13]
	v_mfma_f32_16x16x32_bf16 v[62:65], v[142:145], v[174:177], v[62:65]
	v_mfma_f32_16x16x32_bf16 v[58:61], v[150:153], v[174:177], v[58:61]
	v_mfma_f32_16x16x32_bf16 v[46:49], v[142:145], v[182:185], v[46:49]
	v_mfma_f32_16x16x32_bf16 v[42:45], v[150:153], v[182:185], v[42:45]
	v_mfma_f32_16x16x32_bf16 v[30:33], v[142:145], v[190:193], v[30:33]
	v_mfma_f32_16x16x32_bf16 v[26:29], v[150:153], v[190:193], v[26:29]
	v_mfma_f32_16x16x32_bf16 v[14:17], v[142:145], v[198:201], v[14:17]
	v_mfma_f32_16x16x32_bf16 v[10:13], v[150:153], v[198:201], v[10:13]
	v_mfma_f32_16x16x32_bf16 v[54:57], v[154:157], v[170:173], v[54:57]
	v_mfma_f32_16x16x32_bf16 v[50:53], v[162:165], v[170:173], v[50:53]
	v_mfma_f32_16x16x32_bf16 v[38:41], v[154:157], v[178:181], v[38:41]
	v_mfma_f32_16x16x32_bf16 v[34:37], v[162:165], v[178:181], v[34:37]
	v_mfma_f32_16x16x32_bf16 v[22:25], v[154:157], v[186:189], v[22:25]
	v_mfma_f32_16x16x32_bf16 v[18:21], v[162:165], v[186:189], v[18:21]
	v_mfma_f32_16x16x32_bf16 v[6:9], v[154:157], v[194:197], v[6:9]
	v_mfma_f32_16x16x32_bf16 v[2:5], v[162:165], v[194:197], v[2:5]
	v_mfma_f32_16x16x32_bf16 v[54:57], v[158:161], v[174:177], v[54:57]
	v_mfma_f32_16x16x32_bf16 v[50:53], v[166:169], v[174:177], v[50:53]
	v_mfma_f32_16x16x32_bf16 v[38:41], v[158:161], v[182:185], v[38:41]
	v_mfma_f32_16x16x32_bf16 v[34:37], v[166:169], v[182:185], v[34:37]
	v_mfma_f32_16x16x32_bf16 v[22:25], v[158:161], v[190:193], v[22:25]
	v_mfma_f32_16x16x32_bf16 v[18:21], v[166:169], v[190:193], v[18:21]
	v_mfma_f32_16x16x32_bf16 v[6:9], v[158:161], v[198:201], v[6:9]
	v_mfma_f32_16x16x32_bf16 v[2:5], v[166:169], v[198:201], v[2:5]
	s_barrier
	s_setprio 0
	v_add_u32_e32 v150, 0x18000, v132
	v_add_u32_e32 v166, 0x1c000, v132
	ds_read_b128 v[134:137], v150
	ds_read_b128 v[142:145], v150 offset:1024
	ds_read_b128 v[146:149], v150 offset:2048
	ds_read_b128 v[150:153], v150 offset:3072
	ds_read_b128 v[154:157], v166
	ds_read_b128 v[158:161], v166 offset:1024
	ds_read_b128 v[162:165], v166 offset:2048
	ds_read_b128 v[166:169], v166 offset:3072
	s_add_i32 s63, s64, 0x40000
	s_mov_b32 m0, s41
	s_nop 0
	buffer_load_dwordx4 v130, s[12:15], s63 offen lds
	s_nop 0
	s_mov_b32 m0, s42
	s_nop 0
	buffer_load_dwordx4 v131, s[12:15], s63 offen lds
	ds_read_b128 v[170:173], v133 offset:32768
	ds_read_b128 v[174:177], v133 offset:33792
	ds_read_b128 v[178:181], v133 offset:34816
	ds_read_b128 v[182:185], v133 offset:35840
	ds_read_b128 v[186:189], v133 offset:36864
	ds_read_b128 v[190:193], v133 offset:37888
	ds_read_b128 v[194:197], v133 offset:38912
	ds_read_b128 v[198:201], v133 offset:39936
	s_waitcnt vmcnt(8)
	s_waitcnt lgkmcnt(0)
	s_setprio 1
	s_barrier
	v_mfma_f32_16x16x32_bf16 v[138:141], v[134:137], v[170:173], v[138:141]
	v_mfma_f32_16x16x32_bf16 v[126:129], v[146:149], v[170:173], v[126:129]
	v_mfma_f32_16x16x32_bf16 v[110:113], v[134:137], v[178:181], v[110:113]
	v_mfma_f32_16x16x32_bf16 v[106:109], v[146:149], v[178:181], v[106:109]
	v_mfma_f32_16x16x32_bf16 v[94:97], v[134:137], v[186:189], v[94:97]
	v_mfma_f32_16x16x32_bf16 v[90:93], v[146:149], v[186:189], v[90:93]
	v_mfma_f32_16x16x32_bf16 v[78:81], v[134:137], v[194:197], v[78:81]
	v_mfma_f32_16x16x32_bf16 v[74:77], v[146:149], v[194:197], v[74:77]
	v_mfma_f32_16x16x32_bf16 v[138:141], v[142:145], v[174:177], v[138:141]
	v_mfma_f32_16x16x32_bf16 v[126:129], v[150:153], v[174:177], v[126:129]
	v_mfma_f32_16x16x32_bf16 v[110:113], v[142:145], v[182:185], v[110:113]
	v_mfma_f32_16x16x32_bf16 v[106:109], v[150:153], v[182:185], v[106:109]
	v_mfma_f32_16x16x32_bf16 v[94:97], v[142:145], v[190:193], v[94:97]
	v_mfma_f32_16x16x32_bf16 v[90:93], v[150:153], v[190:193], v[90:93]
	v_mfma_f32_16x16x32_bf16 v[78:81], v[142:145], v[198:201], v[78:81]
	v_mfma_f32_16x16x32_bf16 v[74:77], v[150:153], v[198:201], v[74:77]
	v_mfma_f32_16x16x32_bf16 v[118:121], v[154:157], v[170:173], v[118:121]
	v_mfma_f32_16x16x32_bf16 v[114:117], v[162:165], v[170:173], v[114:117]
	v_mfma_f32_16x16x32_bf16 v[102:105], v[154:157], v[178:181], v[102:105]
	v_mfma_f32_16x16x32_bf16 v[98:101], v[162:165], v[178:181], v[98:101]
	v_mfma_f32_16x16x32_bf16 v[86:89], v[154:157], v[186:189], v[86:89]
	v_mfma_f32_16x16x32_bf16 v[82:85], v[162:165], v[186:189], v[82:85]
	v_mfma_f32_16x16x32_bf16 v[70:73], v[154:157], v[194:197], v[70:73]
	v_mfma_f32_16x16x32_bf16 v[66:69], v[162:165], v[194:197], v[66:69]
	v_mfma_f32_16x16x32_bf16 v[118:121], v[158:161], v[174:177], v[118:121]
	v_mfma_f32_16x16x32_bf16 v[114:117], v[166:169], v[174:177], v[114:117]
	v_mfma_f32_16x16x32_bf16 v[102:105], v[158:161], v[182:185], v[102:105]
	v_mfma_f32_16x16x32_bf16 v[98:101], v[166:169], v[182:185], v[98:101]
	v_mfma_f32_16x16x32_bf16 v[86:89], v[158:161], v[190:193], v[86:89]
	v_mfma_f32_16x16x32_bf16 v[82:85], v[166:169], v[190:193], v[82:85]
	v_mfma_f32_16x16x32_bf16 v[70:73], v[158:161], v[198:201], v[70:73]
	v_mfma_f32_16x16x32_bf16 v[66:69], v[166:169], v[198:201], v[66:69]
	s_barrier
	s_setprio 0
	ds_read_b128 v[170:173], v133 offset:49152
	ds_read_b128 v[174:177], v133 offset:50176
	s_or_b32 s63, s62, 0x80
	s_mov_b32 m0, s43
	s_nop 0
	buffer_load_dwordx4 v130, s[8:11], s63 offen lds
	ds_read_b128 v[178:181], v133 offset:51200
	ds_read_b128 v[182:185], v133 offset:52224
	s_add_i32 s62, s62, 0x40080
	s_mov_b32 m0, s44
	s_nop 0
	buffer_load_dwordx4 v131, s[8:11], s63 offen lds
	ds_read_b128 v[186:189], v133 offset:53248
	ds_read_b128 v[190:193], v133 offset:54272
	s_nop 0
	s_mov_b32 m0, s47
	s_nop 0
	buffer_load_dwordx4 v130, s[8:11], s62 offen lds
	ds_read_b128 v[194:197], v133 offset:55296
	ds_read_b128 v[198:201], v133 offset:56320
	s_nop 0
	s_mov_b32 m0, s48
	s_nop 0
	buffer_load_dwordx4 v131, s[8:11], s62 offen lds
	s_nop 0
	s_mov_b32 m0, s45
	s_nop 0
	buffer_load_dwordx4 v130, s[12:15], s61 offen lds
	s_nop 0
	s_mov_b32 m0, s46
	s_nop 0
	buffer_load_dwordx4 v131, s[12:15], s61 offen lds
	s_waitcnt vmcnt(8)
	s_waitcnt lgkmcnt(0)
	s_setprio 1
	s_barrier
	v_mfma_f32_16x16x32_bf16 v[62:65], v[134:137], v[170:173], v[62:65]
	v_mfma_f32_16x16x32_bf16 v[58:61], v[146:149], v[170:173], v[58:61]
	v_mfma_f32_16x16x32_bf16 v[46:49], v[134:137], v[178:181], v[46:49]
	v_mfma_f32_16x16x32_bf16 v[42:45], v[146:149], v[178:181], v[42:45]
	v_mfma_f32_16x16x32_bf16 v[30:33], v[134:137], v[186:189], v[30:33]
	v_mfma_f32_16x16x32_bf16 v[26:29], v[146:149], v[186:189], v[26:29]
	v_mfma_f32_16x16x32_bf16 v[14:17], v[134:137], v[194:197], v[14:17]
	v_mfma_f32_16x16x32_bf16 v[10:13], v[146:149], v[194:197], v[10:13]
	v_mfma_f32_16x16x32_bf16 v[62:65], v[142:145], v[174:177], v[62:65]
	v_mfma_f32_16x16x32_bf16 v[58:61], v[150:153], v[174:177], v[58:61]
	v_mfma_f32_16x16x32_bf16 v[46:49], v[142:145], v[182:185], v[46:49]
	v_mfma_f32_16x16x32_bf16 v[42:45], v[150:153], v[182:185], v[42:45]
	v_mfma_f32_16x16x32_bf16 v[30:33], v[142:145], v[190:193], v[30:33]
	v_mfma_f32_16x16x32_bf16 v[26:29], v[150:153], v[190:193], v[26:29]
	v_mfma_f32_16x16x32_bf16 v[14:17], v[142:145], v[198:201], v[14:17]
	v_mfma_f32_16x16x32_bf16 v[10:13], v[150:153], v[198:201], v[10:13]
	v_mfma_f32_16x16x32_bf16 v[54:57], v[154:157], v[170:173], v[54:57]
	v_mfma_f32_16x16x32_bf16 v[50:53], v[162:165], v[170:173], v[50:53]
	v_mfma_f32_16x16x32_bf16 v[38:41], v[154:157], v[178:181], v[38:41]
	v_mfma_f32_16x16x32_bf16 v[34:37], v[162:165], v[178:181], v[34:37]
	v_mfma_f32_16x16x32_bf16 v[22:25], v[154:157], v[186:189], v[22:25]
	v_mfma_f32_16x16x32_bf16 v[18:21], v[162:165], v[186:189], v[18:21]
	v_mfma_f32_16x16x32_bf16 v[6:9], v[154:157], v[194:197], v[6:9]
	v_mfma_f32_16x16x32_bf16 v[2:5], v[162:165], v[194:197], v[2:5]
	v_mfma_f32_16x16x32_bf16 v[54:57], v[158:161], v[174:177], v[54:57]
	v_mfma_f32_16x16x32_bf16 v[50:53], v[166:169], v[174:177], v[50:53]
	v_mfma_f32_16x16x32_bf16 v[38:41], v[158:161], v[182:185], v[38:41]
	v_mfma_f32_16x16x32_bf16 v[34:37], v[166:169], v[182:185], v[34:37]
	v_mfma_f32_16x16x32_bf16 v[22:25], v[158:161], v[190:193], v[22:25]
	v_mfma_f32_16x16x32_bf16 v[18:21], v[166:169], v[190:193], v[18:21]
	v_mfma_f32_16x16x32_bf16 v[6:9], v[158:161], v[198:201], v[6:9]
	v_mfma_f32_16x16x32_bf16 v[2:5], v[166:169], v[198:201], v[2:5]
	s_barrier
	s_setprio 0
	s_add_i32 s59, s59, 2
	s_addk_i32 s60, 0x100
	s_cmp_gt_u32 s59, 13
	s_cbranch_scc0 .LBB0_223
	s_andn2_b64 vcc, exec, s[6:7]
	s_cbranch_vccnz .LBB0_215
	v_mov_b32_e32 v2, 0
	s_mov_b32 s18, s52
	s_mov_b32 s29, s53
	s_mov_b32 s34, s3
	s_mov_b32 s39, s2
	s_mov_b32 s51, s54
	v_mov_b32_e32 v3, v2
	v_mov_b32_e32 v4, v2
	v_mov_b32_e32 v5, v2
	v_mov_b32_e32 v6, v2
	v_mov_b32_e32 v7, v2
	v_mov_b32_e32 v8, v2
	v_mov_b32_e32 v9, v2
	v_mov_b32_e32 v18, v2
	v_mov_b32_e32 v19, v2
	v_mov_b32_e32 v20, v2
	v_mov_b32_e32 v21, v2
	v_mov_b32_e32 v22, v2
	v_mov_b32_e32 v23, v2
	v_mov_b32_e32 v24, v2
	v_mov_b32_e32 v25, v2
	v_mov_b32_e32 v34, v2
	v_mov_b32_e32 v35, v2
	v_mov_b32_e32 v36, v2
	v_mov_b32_e32 v37, v2
	v_mov_b32_e32 v38, v2
	v_mov_b32_e32 v39, v2
	v_mov_b32_e32 v40, v2
	v_mov_b32_e32 v41, v2
	v_mov_b32_e32 v50, v2
	v_mov_b32_e32 v51, v2
	v_mov_b32_e32 v52, v2
	v_mov_b32_e32 v53, v2
	v_mov_b32_e32 v54, v2
	v_mov_b32_e32 v55, v2
	v_mov_b32_e32 v56, v2
	v_mov_b32_e32 v57, v2
	v_mov_b32_e32 v10, v2
	v_mov_b32_e32 v11, v2
	v_mov_b32_e32 v12, v2
	v_mov_b32_e32 v13, v2
	v_mov_b32_e32 v14, v2
	v_mov_b32_e32 v15, v2
	v_mov_b32_e32 v16, v2
	v_mov_b32_e32 v17, v2
	v_mov_b32_e32 v26, v2
	v_mov_b32_e32 v27, v2
	v_mov_b32_e32 v28, v2
	v_mov_b32_e32 v29, v2
	v_mov_b32_e32 v30, v2
	v_mov_b32_e32 v31, v2
	v_mov_b32_e32 v32, v2
	v_mov_b32_e32 v33, v2
	v_mov_b32_e32 v42, v2
	v_mov_b32_e32 v43, v2
	v_mov_b32_e32 v44, v2
	v_mov_b32_e32 v45, v2
	v_mov_b32_e32 v46, v2
	v_mov_b32_e32 v47, v2
	v_mov_b32_e32 v48, v2
	v_mov_b32_e32 v49, v2
	v_mov_b32_e32 v58, v2
	v_mov_b32_e32 v59, v2
	v_mov_b32_e32 v60, v2
	v_mov_b32_e32 v61, v2
	v_mov_b32_e32 v62, v2
	v_mov_b32_e32 v63, v2
	v_mov_b32_e32 v64, v2
	v_mov_b32_e32 v65, v2
	v_mov_b32_e32 v66, v2
	v_mov_b32_e32 v67, v2
	v_mov_b32_e32 v68, v2
	v_mov_b32_e32 v69, v2
	v_mov_b32_e32 v70, v2
	v_mov_b32_e32 v71, v2
	v_mov_b32_e32 v72, v2
	v_mov_b32_e32 v73, v2
	v_mov_b32_e32 v82, v2
	v_mov_b32_e32 v83, v2
	v_mov_b32_e32 v84, v2
	v_mov_b32_e32 v85, v2
	v_mov_b32_e32 v86, v2
	v_mov_b32_e32 v87, v2
	v_mov_b32_e32 v88, v2
	v_mov_b32_e32 v89, v2
	v_mov_b32_e32 v98, v2
	v_mov_b32_e32 v99, v2
	v_mov_b32_e32 v100, v2
	v_mov_b32_e32 v101, v2
	v_mov_b32_e32 v102, v2
	v_mov_b32_e32 v103, v2
	v_mov_b32_e32 v104, v2
	v_mov_b32_e32 v105, v2
	v_mov_b32_e32 v114, v2
	v_mov_b32_e32 v115, v2
	v_mov_b32_e32 v116, v2
	v_mov_b32_e32 v117, v2
	v_mov_b32_e32 v118, v2
	v_mov_b32_e32 v119, v2
	v_mov_b32_e32 v120, v2
	v_mov_b32_e32 v121, v2
	v_mov_b32_e32 v74, v2
	v_mov_b32_e32 v75, v2
	v_mov_b32_e32 v76, v2
	v_mov_b32_e32 v77, v2
	v_mov_b32_e32 v78, v2
	v_mov_b32_e32 v79, v2
	v_mov_b32_e32 v80, v2
	v_mov_b32_e32 v81, v2
	v_mov_b32_e32 v90, v2
	v_mov_b32_e32 v91, v2
	v_mov_b32_e32 v92, v2
	v_mov_b32_e32 v93, v2
	v_mov_b32_e32 v94, v2
	v_mov_b32_e32 v95, v2
	v_mov_b32_e32 v96, v2
	v_mov_b32_e32 v97, v2
	v_mov_b32_e32 v106, v2
	v_mov_b32_e32 v107, v2
	v_mov_b32_e32 v108, v2
	v_mov_b32_e32 v109, v2
	v_mov_b32_e32 v110, v2
	v_mov_b32_e32 v111, v2
	v_mov_b32_e32 v112, v2
	v_mov_b32_e32 v113, v2
	v_mov_b32_e32 v126, v2
	v_mov_b32_e32 v127, v2
	v_mov_b32_e32 v128, v2
	v_mov_b32_e32 v129, v2
	v_mov_b32_e32 v138, v2
	v_mov_b32_e32 v139, v2
	v_mov_b32_e32 v140, v2
	v_mov_b32_e32 v141, v2
	s_branch .LBB0_215

.LBB0_353:
	ds_read_b128 v[136:139], v153
	ds_read_b128 v[140:143], v153 offset:1024
	ds_read_b128 v[158:161], v153 offset:2048
	ds_read_b128 v[162:165], v153 offset:3072
	ds_read_b128 v[166:169], v154
	ds_read_b128 v[170:173], v154 offset:1024
	ds_read_b128 v[174:177], v154 offset:2048
	ds_read_b128 v[178:181], v154 offset:3072
	s_add_i32 s66, s63, 0xfffe0080
	s_cmp_eq_u32 s65, 4
	s_cselect_b32 s68, s1, s66
	s_cselect_b32 s67, s62, s64
	s_or_b32 s66, s68, 0x80
	s_mov_b32 m0, s48
	s_nop 0
	buffer_load_dwordx4 v147, s[12:15], s63 offen lds
	s_nop 0
	s_mov_b32 m0, s49
	s_nop 0
	buffer_load_dwordx4 v148, s[12:15], s63 offen lds
	ds_read_b128 v[182:185], v155
	ds_read_b128 v[186:189], v155 offset:1024
	ds_read_b128 v[190:193], v155 offset:2048
	ds_read_b128 v[194:197], v155 offset:3072
	ds_read_b128 v[198:201], v155 offset:4096
	ds_read_b128 v[202:205], v155 offset:5120
	ds_read_b128 v[206:209], v155 offset:6144
	ds_read_b128 v[210:213], v155 offset:7168
	s_waitcnt vmcnt(8)
	s_waitcnt lgkmcnt(0)
	s_setprio 1
	s_barrier
	v_mfma_i32_16x16x64_i8 v[126:129], v[136:139], v[182:185], v[126:129]
	v_mfma_i32_16x16x64_i8 v[122:125], v[158:161], v[182:185], v[122:125]
	v_mfma_i32_16x16x64_i8 v[118:121], v[136:139], v[190:193], v[118:121]
	v_mfma_i32_16x16x64_i8 v[114:117], v[158:161], v[190:193], v[114:117]
	v_mfma_i32_16x16x64_i8 v[110:113], v[136:139], v[198:201], v[110:113]
	v_mfma_i32_16x16x64_i8 v[106:109], v[158:161], v[198:201], v[106:109]
	v_mfma_i32_16x16x64_i8 v[102:105], v[136:139], v[206:209], v[102:105]
	v_mfma_i32_16x16x64_i8 v[98:101], v[158:161], v[206:209], v[98:101]
	v_mfma_i32_16x16x64_i8 v[126:129], v[140:143], v[186:189], v[126:129]
	v_mfma_i32_16x16x64_i8 v[122:125], v[162:165], v[186:189], v[122:125]
	v_mfma_i32_16x16x64_i8 v[118:121], v[140:143], v[194:197], v[118:121]
	v_mfma_i32_16x16x64_i8 v[114:117], v[162:165], v[194:197], v[114:117]
	v_mfma_i32_16x16x64_i8 v[110:113], v[140:143], v[202:205], v[110:113]
	v_mfma_i32_16x16x64_i8 v[106:109], v[162:165], v[202:205], v[106:109]
	v_mfma_i32_16x16x64_i8 v[102:105], v[140:143], v[210:213], v[102:105]
	v_mfma_i32_16x16x64_i8 v[98:101], v[162:165], v[210:213], v[98:101]
	v_mfma_i32_16x16x64_i8 v[94:97], v[166:169], v[182:185], v[94:97]
	v_mfma_i32_16x16x64_i8 v[90:93], v[174:177], v[182:185], v[90:93]
	v_mfma_i32_16x16x64_i8 v[86:89], v[166:169], v[190:193], v[86:89]
	v_mfma_i32_16x16x64_i8 v[82:85], v[174:177], v[190:193], v[82:85]
	v_mfma_i32_16x16x64_i8 v[78:81], v[166:169], v[198:201], v[78:81]
	v_mfma_i32_16x16x64_i8 v[74:77], v[174:177], v[198:201], v[74:77]
	v_mfma_i32_16x16x64_i8 v[70:73], v[166:169], v[206:209], v[70:73]
	v_mfma_i32_16x16x64_i8 v[66:69], v[174:177], v[206:209], v[66:69]
	v_mfma_i32_16x16x64_i8 v[94:97], v[170:173], v[186:189], v[94:97]
	v_mfma_i32_16x16x64_i8 v[90:93], v[178:181], v[186:189], v[90:93]
	v_mfma_i32_16x16x64_i8 v[86:89], v[170:173], v[194:197], v[86:89]
	v_mfma_i32_16x16x64_i8 v[82:85], v[178:181], v[194:197], v[82:85]
	v_mfma_i32_16x16x64_i8 v[78:81], v[170:173], v[202:205], v[78:81]
	v_mfma_i32_16x16x64_i8 v[74:77], v[178:181], v[202:205], v[74:77]
	v_mfma_i32_16x16x64_i8 v[70:73], v[170:173], v[210:213], v[70:73]
	v_mfma_i32_16x16x64_i8 v[66:69], v[178:181], v[210:213], v[66:69]
	s_barrier
	s_setprio 0
	ds_read_b128 v[182:185], v155 offset:16384
	ds_read_b128 v[186:189], v155 offset:17408
	s_mov_b32 m0, s34
	s_nop 0
	buffer_load_dwordx4 v145, s[8:11], s67 offen lds
	ds_read_b128 v[190:193], v155 offset:18432
	ds_read_b128 v[194:197], v155 offset:19456
	s_add_i32 s69, s67, 0x20000
	s_mov_b32 m0, s35
	s_nop 0
	buffer_load_dwordx4 v146, s[8:11], s67 offen lds
	ds_read_b128 v[198:201], v155 offset:20480
	ds_read_b128 v[202:205], v155 offset:21504
	s_nop 0
	s_mov_b32 m0, s36
	s_nop 0
	buffer_load_dwordx4 v145, s[8:11], s69 offen lds
	ds_read_b128 v[206:209], v155 offset:22528
	ds_read_b128 v[210:213], v155 offset:23552
	s_nop 0
	s_mov_b32 m0, s37
	s_nop 0
	buffer_load_dwordx4 v146, s[8:11], s69 offen lds
	s_nop 0
	s_mov_b32 m0, s33
	s_nop 0
	buffer_load_dwordx4 v147, s[12:15], s68 offen lds
	s_nop 0
	s_mov_b32 m0, s2
	s_nop 0
	buffer_load_dwordx4 v148, s[12:15], s68 offen lds
	s_waitcnt vmcnt(8)
	s_waitcnt lgkmcnt(0)
	s_setprio 1
	s_barrier
	v_mfma_i32_16x16x64_i8 v[62:65], v[136:139], v[182:185], v[62:65]
	v_mfma_i32_16x16x64_i8 v[58:61], v[158:161], v[182:185], v[58:61]
	v_mfma_i32_16x16x64_i8 v[54:57], v[136:139], v[190:193], v[54:57]
	v_mfma_i32_16x16x64_i8 v[50:53], v[158:161], v[190:193], v[50:53]
	v_mfma_i32_16x16x64_i8 v[46:49], v[136:139], v[198:201], v[46:49]
	v_mfma_i32_16x16x64_i8 v[42:45], v[158:161], v[198:201], v[42:45]
	v_mfma_i32_16x16x64_i8 v[38:41], v[136:139], v[206:209], v[38:41]
	v_mfma_i32_16x16x64_i8 v[34:37], v[158:161], v[206:209], v[34:37]
	v_mfma_i32_16x16x64_i8 v[62:65], v[140:143], v[186:189], v[62:65]
	v_mfma_i32_16x16x64_i8 v[58:61], v[162:165], v[186:189], v[58:61]
	v_mfma_i32_16x16x64_i8 v[54:57], v[140:143], v[194:197], v[54:57]
	v_mfma_i32_16x16x64_i8 v[50:53], v[162:165], v[194:197], v[50:53]
	v_mfma_i32_16x16x64_i8 v[46:49], v[140:143], v[202:205], v[46:49]
	v_mfma_i32_16x16x64_i8 v[42:45], v[162:165], v[202:205], v[42:45]
	v_mfma_i32_16x16x64_i8 v[38:41], v[140:143], v[210:213], v[38:41]
	v_mfma_i32_16x16x64_i8 v[34:37], v[162:165], v[210:213], v[34:37]
	v_mfma_i32_16x16x64_i8 v[30:33], v[166:169], v[182:185], v[30:33]
	v_mfma_i32_16x16x64_i8 v[26:29], v[174:177], v[182:185], v[26:29]
	v_mfma_i32_16x16x64_i8 v[22:25], v[166:169], v[190:193], v[22:25]
	v_mfma_i32_16x16x64_i8 v[18:21], v[174:177], v[190:193], v[18:21]
	v_mfma_i32_16x16x64_i8 v[14:17], v[166:169], v[198:201], v[14:17]
	v_mfma_i32_16x16x64_i8 v[10:13], v[174:177], v[198:201], v[10:13]
	v_mfma_i32_16x16x64_i8 v[6:9], v[166:169], v[206:209], v[6:9]
	v_mfma_i32_16x16x64_i8 v[2:5], v[174:177], v[206:209], v[2:5]
	v_mfma_i32_16x16x64_i8 v[30:33], v[170:173], v[186:189], v[30:33]
	v_mfma_i32_16x16x64_i8 v[26:29], v[178:181], v[186:189], v[26:29]
	v_mfma_i32_16x16x64_i8 v[22:25], v[170:173], v[194:197], v[22:25]
	v_mfma_i32_16x16x64_i8 v[18:21], v[178:181], v[194:197], v[18:21]
	v_mfma_i32_16x16x64_i8 v[14:17], v[170:173], v[202:205], v[14:17]
	v_mfma_i32_16x16x64_i8 v[10:13], v[178:181], v[202:205], v[10:13]
	v_mfma_i32_16x16x64_i8 v[6:9], v[170:173], v[210:213], v[6:9]
	v_mfma_i32_16x16x64_i8 v[2:5], v[178:181], v[210:213], v[2:5]
	s_barrier
	s_setprio 0
	ds_read_b128 v[136:139], v156
	ds_read_b128 v[140:143], v156 offset:1024
	ds_read_b128 v[158:161], v156 offset:2048
	ds_read_b128 v[162:165], v156 offset:3072
	ds_read_b128 v[166:169], v157
	ds_read_b128 v[170:173], v157 offset:1024
	ds_read_b128 v[174:177], v157 offset:2048
	ds_read_b128 v[178:181], v157 offset:3072
	s_add_i32 s68, s68, 0x20000
	s_mov_b32 m0, s3
	s_nop 0
	buffer_load_dwordx4 v147, s[12:15], s68 offen lds
	s_nop 0
	s_mov_b32 m0, s38
	s_nop 0
	buffer_load_dwordx4 v148, s[12:15], s68 offen lds
	ds_read_b128 v[182:185], v155 offset:32768
	ds_read_b128 v[186:189], v155 offset:33792
	ds_read_b128 v[190:193], v155 offset:34816
	ds_read_b128 v[194:197], v155 offset:35840
	ds_read_b128 v[198:201], v155 offset:36864
	ds_read_b128 v[202:205], v155 offset:37888
	ds_read_b128 v[206:209], v155 offset:38912
	ds_read_b128 v[210:213], v155 offset:39936
	s_waitcnt vmcnt(8)
	s_waitcnt lgkmcnt(0)
	s_setprio 1
	s_barrier
	v_mfma_i32_16x16x64_i8 v[126:129], v[136:139], v[182:185], v[126:129]
	v_mfma_i32_16x16x64_i8 v[122:125], v[158:161], v[182:185], v[122:125]
	v_mfma_i32_16x16x64_i8 v[118:121], v[136:139], v[190:193], v[118:121]
	v_mfma_i32_16x16x64_i8 v[114:117], v[158:161], v[190:193], v[114:117]
	v_mfma_i32_16x16x64_i8 v[110:113], v[136:139], v[198:201], v[110:113]
	v_mfma_i32_16x16x64_i8 v[106:109], v[158:161], v[198:201], v[106:109]
	v_mfma_i32_16x16x64_i8 v[102:105], v[136:139], v[206:209], v[102:105]
	v_mfma_i32_16x16x64_i8 v[98:101], v[158:161], v[206:209], v[98:101]
	v_mfma_i32_16x16x64_i8 v[126:129], v[140:143], v[186:189], v[126:129]
	v_mfma_i32_16x16x64_i8 v[122:125], v[162:165], v[186:189], v[122:125]
	v_mfma_i32_16x16x64_i8 v[118:121], v[140:143], v[194:197], v[118:121]
	v_mfma_i32_16x16x64_i8 v[114:117], v[162:165], v[194:197], v[114:117]
	v_mfma_i32_16x16x64_i8 v[110:113], v[140:143], v[202:205], v[110:113]
	v_mfma_i32_16x16x64_i8 v[106:109], v[162:165], v[202:205], v[106:109]
	v_mfma_i32_16x16x64_i8 v[102:105], v[140:143], v[210:213], v[102:105]
	v_mfma_i32_16x16x64_i8 v[98:101], v[162:165], v[210:213], v[98:101]
	v_mfma_i32_16x16x64_i8 v[94:97], v[166:169], v[182:185], v[94:97]
	v_mfma_i32_16x16x64_i8 v[90:93], v[174:177], v[182:185], v[90:93]
	v_mfma_i32_16x16x64_i8 v[86:89], v[166:169], v[190:193], v[86:89]
	v_mfma_i32_16x16x64_i8 v[82:85], v[174:177], v[190:193], v[82:85]
	v_mfma_i32_16x16x64_i8 v[78:81], v[166:169], v[198:201], v[78:81]
	v_mfma_i32_16x16x64_i8 v[74:77], v[174:177], v[198:201], v[74:77]
	v_mfma_i32_16x16x64_i8 v[70:73], v[166:169], v[206:209], v[70:73]
	v_mfma_i32_16x16x64_i8 v[66:69], v[174:177], v[206:209], v[66:69]
	v_mfma_i32_16x16x64_i8 v[94:97], v[170:173], v[186:189], v[94:97]
	v_mfma_i32_16x16x64_i8 v[90:93], v[178:181], v[186:189], v[90:93]
	v_mfma_i32_16x16x64_i8 v[86:89], v[170:173], v[194:197], v[86:89]
	v_mfma_i32_16x16x64_i8 v[82:85], v[178:181], v[194:197], v[82:85]
	v_mfma_i32_16x16x64_i8 v[78:81], v[170:173], v[202:205], v[78:81]
	v_mfma_i32_16x16x64_i8 v[74:77], v[178:181], v[202:205], v[74:77]
	v_mfma_i32_16x16x64_i8 v[70:73], v[170:173], v[210:213], v[70:73]
	v_mfma_i32_16x16x64_i8 v[66:69], v[178:181], v[210:213], v[66:69]
	s_barrier
	s_setprio 0
	ds_read_b128 v[182:185], v155 offset:49152
	ds_read_b128 v[186:189], v155 offset:50176
	s_or_b32 s68, s67, 0x80
	s_mov_b32 m0, s41
	s_nop 0
	buffer_load_dwordx4 v145, s[8:11], s68 offen lds
	ds_read_b128 v[190:193], v155 offset:51200
	ds_read_b128 v[194:197], v155 offset:52224
	s_add_i32 s67, s67, 0x20080
	s_mov_b32 m0, s42
	s_nop 0
	buffer_load_dwordx4 v146, s[8:11], s68 offen lds
	ds_read_b128 v[198:201], v155 offset:53248
	ds_read_b128 v[202:205], v155 offset:54272
	s_nop 0
	s_mov_b32 m0, s45
	s_nop 0
	buffer_load_dwordx4 v145, s[8:11], s67 offen lds
	ds_read_b128 v[206:209], v155 offset:55296
	ds_read_b128 v[210:213], v155 offset:56320
	s_nop 0
	s_mov_b32 m0, s46
	s_nop 0
	buffer_load_dwordx4 v146, s[8:11], s67 offen lds
	s_nop 0
	s_mov_b32 m0, s43
	s_nop 0
	buffer_load_dwordx4 v147, s[12:15], s66 offen lds
	s_nop 0
	s_mov_b32 m0, s44
	s_nop 0
	buffer_load_dwordx4 v148, s[12:15], s66 offen lds
	s_waitcnt vmcnt(8)
	s_waitcnt lgkmcnt(0)
	s_setprio 1
	s_barrier
	v_mfma_i32_16x16x64_i8 v[62:65], v[136:139], v[182:185], v[62:65]
	v_mfma_i32_16x16x64_i8 v[58:61], v[158:161], v[182:185], v[58:61]
	v_mfma_i32_16x16x64_i8 v[54:57], v[136:139], v[190:193], v[54:57]
	v_mfma_i32_16x16x64_i8 v[50:53], v[158:161], v[190:193], v[50:53]
	v_mfma_i32_16x16x64_i8 v[46:49], v[136:139], v[198:201], v[46:49]
	v_mfma_i32_16x16x64_i8 v[42:45], v[158:161], v[198:201], v[42:45]
	v_mfma_i32_16x16x64_i8 v[38:41], v[136:139], v[206:209], v[38:41]
	v_mfma_i32_16x16x64_i8 v[34:37], v[158:161], v[206:209], v[34:37]
	v_mfma_i32_16x16x64_i8 v[62:65], v[140:143], v[186:189], v[62:65]
	v_mfma_i32_16x16x64_i8 v[58:61], v[162:165], v[186:189], v[58:61]
	v_mfma_i32_16x16x64_i8 v[54:57], v[140:143], v[194:197], v[54:57]
	v_mfma_i32_16x16x64_i8 v[50:53], v[162:165], v[194:197], v[50:53]
	v_mfma_i32_16x16x64_i8 v[46:49], v[140:143], v[202:205], v[46:49]
	v_mfma_i32_16x16x64_i8 v[42:45], v[162:165], v[202:205], v[42:45]
	v_mfma_i32_16x16x64_i8 v[38:41], v[140:143], v[210:213], v[38:41]
	v_mfma_i32_16x16x64_i8 v[34:37], v[162:165], v[210:213], v[34:37]
	v_mfma_i32_16x16x64_i8 v[30:33], v[166:169], v[182:185], v[30:33]
	v_mfma_i32_16x16x64_i8 v[26:29], v[174:177], v[182:185], v[26:29]
	v_mfma_i32_16x16x64_i8 v[22:25], v[166:169], v[190:193], v[22:25]
	v_mfma_i32_16x16x64_i8 v[18:21], v[174:177], v[190:193], v[18:21]
	v_mfma_i32_16x16x64_i8 v[14:17], v[166:169], v[198:201], v[14:17]
	v_mfma_i32_16x16x64_i8 v[10:13], v[174:177], v[198:201], v[10:13]
	v_mfma_i32_16x16x64_i8 v[6:9], v[166:169], v[206:209], v[6:9]
	v_mfma_i32_16x16x64_i8 v[2:5], v[174:177], v[206:209], v[2:5]
	v_mfma_i32_16x16x64_i8 v[30:33], v[170:173], v[186:189], v[30:33]
	v_mfma_i32_16x16x64_i8 v[26:29], v[178:181], v[186:189], v[26:29]
	v_mfma_i32_16x16x64_i8 v[22:25], v[170:173], v[194:197], v[22:25]
	v_mfma_i32_16x16x64_i8 v[18:21], v[178:181], v[194:197], v[18:21]
	v_mfma_i32_16x16x64_i8 v[14:17], v[170:173], v[202:205], v[14:17]
	v_mfma_i32_16x16x64_i8 v[10:13], v[178:181], v[202:205], v[10:13]
	v_mfma_i32_16x16x64_i8 v[6:9], v[170:173], v[210:213], v[6:9]
	v_mfma_i32_16x16x64_i8 v[2:5], v[178:181], v[210:213], v[2:5]
	s_barrier
	s_setprio 0
	s_add_i32 s65, s65, 2
	s_addk_i32 s63, 0x100
	s_addk_i32 s64, 0x100
	s_cmp_gt_u32 s65, 5
	s_cbranch_scc0 .LBB0_353
	s_and_b64 vcc, exec, s[24:25]
	s_cbranch_vccz .LBB0_356
	s_barrier

.LBB0_467:
	v_add_u32_e32 v147, 0x10000, v132
	ds_read_b128 v[138:141], v147
	ds_read_b128 v[142:145], v147 offset:1024
	ds_read_b128 v[148:151], v147 offset:2048
	ds_read_b128 v[152:155], v147 offset:3072
	v_add_u32_e32 v147, 0x14000, v132
	ds_read_b128 v[156:159], v147
	ds_read_b128 v[160:163], v147 offset:1024
	ds_read_b128 v[164:167], v147 offset:2048
	ds_read_b128 v[168:171], v147 offset:3072
	s_add_i32 s59, s3, s1
	s_add_i32 s58, s33, s1
	s_add_i32 s55, s59, 0x1600
	s_addk_i32 s58, 0x1600
	s_cmp_eq_u32 s1, 0
	s_cselect_b32 s60, s53, s55
	s_cselect_b32 s58, s54, s58
	s_add_i32 s55, s60, 0x80
	s_add_i32 s59, s59, 0xb1580
	s_mov_b32 m0, s46
	s_nop 0
	buffer_load_dwordx4 v130, s[12:15], s59 offen lds
	s_nop 0
	s_mov_b32 m0, s47
	s_nop 0
	buffer_load_dwordx4 v131, s[12:15], s59 offen lds
	ds_read_b128 v[172:175], v133
	ds_read_b128 v[176:179], v133 offset:1024
	ds_read_b128 v[180:183], v133 offset:2048
	ds_read_b128 v[184:187], v133 offset:3072
	ds_read_b128 v[188:191], v133 offset:4096
	ds_read_b128 v[192:195], v133 offset:5120
	ds_read_b128 v[196:199], v133 offset:6144
	ds_read_b128 v[200:203], v133 offset:7168
	s_waitcnt vmcnt(8)
	s_waitcnt lgkmcnt(0)
	s_setprio 1
	s_barrier
	v_mfma_f32_16x16x32_bf16 v[134:137], v[138:141], v[172:175], v[134:137]
	v_mfma_f32_16x16x32_bf16 v[122:125], v[148:151], v[172:175], v[122:125]
	v_mfma_f32_16x16x32_bf16 v[110:113], v[138:141], v[180:183], v[110:113]
	v_mfma_f32_16x16x32_bf16 v[106:109], v[148:151], v[180:183], v[106:109]
	v_mfma_f32_16x16x32_bf16 v[94:97], v[138:141], v[188:191], v[94:97]
	v_mfma_f32_16x16x32_bf16 v[90:93], v[148:151], v[188:191], v[90:93]
	v_mfma_f32_16x16x32_bf16 v[78:81], v[138:141], v[196:199], v[78:81]
	v_mfma_f32_16x16x32_bf16 v[74:77], v[148:151], v[196:199], v[74:77]
	v_mfma_f32_16x16x32_bf16 v[134:137], v[142:145], v[176:179], v[134:137]
	v_mfma_f32_16x16x32_bf16 v[122:125], v[152:155], v[176:179], v[122:125]
	v_mfma_f32_16x16x32_bf16 v[110:113], v[142:145], v[184:187], v[110:113]
	v_mfma_f32_16x16x32_bf16 v[106:109], v[152:155], v[184:187], v[106:109]
	v_mfma_f32_16x16x32_bf16 v[94:97], v[142:145], v[192:195], v[94:97]
	v_mfma_f32_16x16x32_bf16 v[90:93], v[152:155], v[192:195], v[90:93]
	v_mfma_f32_16x16x32_bf16 v[78:81], v[142:145], v[200:203], v[78:81]
	v_mfma_f32_16x16x32_bf16 v[74:77], v[152:155], v[200:203], v[74:77]
	v_mfma_f32_16x16x32_bf16 v[118:121], v[156:159], v[172:175], v[118:121]
	v_mfma_f32_16x16x32_bf16 v[114:117], v[164:167], v[172:175], v[114:117]
	v_mfma_f32_16x16x32_bf16 v[102:105], v[156:159], v[180:183], v[102:105]
	v_mfma_f32_16x16x32_bf16 v[98:101], v[164:167], v[180:183], v[98:101]
	v_mfma_f32_16x16x32_bf16 v[86:89], v[156:159], v[188:191], v[86:89]
	v_mfma_f32_16x16x32_bf16 v[82:85], v[164:167], v[188:191], v[82:85]
	v_mfma_f32_16x16x32_bf16 v[70:73], v[156:159], v[196:199], v[70:73]
	v_mfma_f32_16x16x32_bf16 v[66:69], v[164:167], v[196:199], v[66:69]
	v_mfma_f32_16x16x32_bf16 v[118:121], v[160:163], v[176:179], v[118:121]
	v_mfma_f32_16x16x32_bf16 v[114:117], v[168:171], v[176:179], v[114:117]
	v_mfma_f32_16x16x32_bf16 v[102:105], v[160:163], v[184:187], v[102:105]
	v_mfma_f32_16x16x32_bf16 v[98:101], v[168:171], v[184:187], v[98:101]
	v_mfma_f32_16x16x32_bf16 v[86:89], v[160:163], v[192:195], v[86:89]
	v_mfma_f32_16x16x32_bf16 v[82:85], v[168:171], v[192:195], v[82:85]
	v_mfma_f32_16x16x32_bf16 v[70:73], v[160:163], v[200:203], v[70:73]
	v_mfma_f32_16x16x32_bf16 v[66:69], v[168:171], v[200:203], v[66:69]
	s_barrier
	s_setprio 0
	ds_read_b128 v[172:175], v133 offset:16384
	ds_read_b128 v[176:179], v133 offset:17408
	s_mov_b32 m0, s29
	s_nop 0
	buffer_load_dwordx4 v130, s[8:11], s58 offen lds
	ds_read_b128 v[180:183], v133 offset:18432
	ds_read_b128 v[184:187], v133 offset:19456
	s_add_i32 s59, s58, 0xb0000
	s_mov_b32 m0, s34
	s_nop 0
	buffer_load_dwordx4 v131, s[8:11], s58 offen lds
	ds_read_b128 v[188:191], v133 offset:20480
	ds_read_b128 v[192:195], v133 offset:21504
	s_nop 0
	s_mov_b32 m0, s35
	s_nop 0
	buffer_load_dwordx4 v130, s[8:11], s59 offen lds
	ds_read_b128 v[196:199], v133 offset:22528
	ds_read_b128 v[200:203], v133 offset:23552
	s_nop 0
	s_mov_b32 m0, s36
	s_nop 0
	buffer_load_dwordx4 v131, s[8:11], s59 offen lds
	s_nop 0
	s_mov_b32 m0, s28
	s_nop 0
	buffer_load_dwordx4 v130, s[12:15], s60 offen lds
	s_nop 0
	s_mov_b32 m0, s37
	s_nop 0
	buffer_load_dwordx4 v131, s[12:15], s60 offen lds
	s_waitcnt vmcnt(8)
	s_waitcnt lgkmcnt(0)
	s_setprio 1
	s_barrier
	v_mfma_f32_16x16x32_bf16 v[62:65], v[138:141], v[172:175], v[62:65]
	v_mfma_f32_16x16x32_bf16 v[58:61], v[148:151], v[172:175], v[58:61]
	v_mfma_f32_16x16x32_bf16 v[46:49], v[138:141], v[180:183], v[46:49]
	v_mfma_f32_16x16x32_bf16 v[42:45], v[148:151], v[180:183], v[42:45]
	v_mfma_f32_16x16x32_bf16 v[30:33], v[138:141], v[188:191], v[30:33]
	v_mfma_f32_16x16x32_bf16 v[26:29], v[148:151], v[188:191], v[26:29]
	v_mfma_f32_16x16x32_bf16 v[14:17], v[138:141], v[196:199], v[14:17]
	v_mfma_f32_16x16x32_bf16 v[10:13], v[148:151], v[196:199], v[10:13]
	v_mfma_f32_16x16x32_bf16 v[62:65], v[142:145], v[176:179], v[62:65]
	v_mfma_f32_16x16x32_bf16 v[58:61], v[152:155], v[176:179], v[58:61]
	v_mfma_f32_16x16x32_bf16 v[46:49], v[142:145], v[184:187], v[46:49]
	v_mfma_f32_16x16x32_bf16 v[42:45], v[152:155], v[184:187], v[42:45]
	v_mfma_f32_16x16x32_bf16 v[30:33], v[142:145], v[192:195], v[30:33]
	v_mfma_f32_16x16x32_bf16 v[26:29], v[152:155], v[192:195], v[26:29]
	v_mfma_f32_16x16x32_bf16 v[14:17], v[142:145], v[200:203], v[14:17]
	v_mfma_f32_16x16x32_bf16 v[10:13], v[152:155], v[200:203], v[10:13]
	v_mfma_f32_16x16x32_bf16 v[54:57], v[156:159], v[172:175], v[54:57]
	v_mfma_f32_16x16x32_bf16 v[50:53], v[164:167], v[172:175], v[50:53]
	v_mfma_f32_16x16x32_bf16 v[38:41], v[156:159], v[180:183], v[38:41]
	v_mfma_f32_16x16x32_bf16 v[34:37], v[164:167], v[180:183], v[34:37]
	v_mfma_f32_16x16x32_bf16 v[22:25], v[156:159], v[188:191], v[22:25]
	v_mfma_f32_16x16x32_bf16 v[18:21], v[164:167], v[188:191], v[18:21]
	v_mfma_f32_16x16x32_bf16 v[6:9], v[156:159], v[196:199], v[6:9]
	v_mfma_f32_16x16x32_bf16 v[2:5], v[164:167], v[196:199], v[2:5]
	v_mfma_f32_16x16x32_bf16 v[54:57], v[160:163], v[176:179], v[54:57]
	v_mfma_f32_16x16x32_bf16 v[50:53], v[168:171], v[176:179], v[50:53]
	v_mfma_f32_16x16x32_bf16 v[38:41], v[160:163], v[184:187], v[38:41]
	v_mfma_f32_16x16x32_bf16 v[34:37], v[168:171], v[184:187], v[34:37]
	v_mfma_f32_16x16x32_bf16 v[22:25], v[160:163], v[192:195], v[22:25]
	v_mfma_f32_16x16x32_bf16 v[18:21], v[168:171], v[192:195], v[18:21]
	v_mfma_f32_16x16x32_bf16 v[6:9], v[160:163], v[200:203], v[6:9]
	v_mfma_f32_16x16x32_bf16 v[2:5], v[168:171], v[200:203], v[2:5]
	s_barrier
	s_setprio 0
	v_add_u32_e32 v147, 0x18000, v132
	ds_read_b128 v[138:141], v147
	ds_read_b128 v[142:145], v147 offset:1024
	ds_read_b128 v[148:151], v147 offset:2048
	ds_read_b128 v[152:155], v147 offset:3072
	v_add_u32_e32 v147, 0x1c000, v132
	ds_read_b128 v[156:159], v147
	ds_read_b128 v[160:163], v147 offset:1024
	ds_read_b128 v[164:167], v147 offset:2048
	ds_read_b128 v[168:171], v147 offset:3072
	s_add_i32 s59, s60, 0xb0000
	s_mov_b32 m0, s38
	s_nop 0
	buffer_load_dwordx4 v130, s[12:15], s59 offen lds
	s_nop 0
	s_mov_b32 m0, s39
	s_nop 0
	buffer_load_dwordx4 v131, s[12:15], s59 offen lds
	ds_read_b128 v[172:175], v133 offset:32768
	ds_read_b128 v[176:179], v133 offset:33792
	ds_read_b128 v[180:183], v133 offset:34816
	ds_read_b128 v[184:187], v133 offset:35840
	ds_read_b128 v[188:191], v133 offset:36864
	ds_read_b128 v[192:195], v133 offset:37888
	ds_read_b128 v[196:199], v133 offset:38912
	ds_read_b128 v[200:203], v133 offset:39936
	s_waitcnt vmcnt(8)
	s_waitcnt lgkmcnt(0)
	s_setprio 1
	s_barrier
	v_mfma_f32_16x16x32_bf16 v[134:137], v[138:141], v[172:175], v[134:137]
	v_mfma_f32_16x16x32_bf16 v[122:125], v[148:151], v[172:175], v[122:125]
	v_mfma_f32_16x16x32_bf16 v[110:113], v[138:141], v[180:183], v[110:113]
	v_mfma_f32_16x16x32_bf16 v[106:109], v[148:151], v[180:183], v[106:109]
	v_mfma_f32_16x16x32_bf16 v[94:97], v[138:141], v[188:191], v[94:97]
	v_mfma_f32_16x16x32_bf16 v[90:93], v[148:151], v[188:191], v[90:93]
	v_mfma_f32_16x16x32_bf16 v[78:81], v[138:141], v[196:199], v[78:81]
	v_mfma_f32_16x16x32_bf16 v[74:77], v[148:151], v[196:199], v[74:77]
	v_mfma_f32_16x16x32_bf16 v[134:137], v[142:145], v[176:179], v[134:137]
	v_mfma_f32_16x16x32_bf16 v[122:125], v[152:155], v[176:179], v[122:125]
	v_mfma_f32_16x16x32_bf16 v[110:113], v[142:145], v[184:187], v[110:113]
	v_mfma_f32_16x16x32_bf16 v[106:109], v[152:155], v[184:187], v[106:109]
	v_mfma_f32_16x16x32_bf16 v[94:97], v[142:145], v[192:195], v[94:97]
	v_mfma_f32_16x16x32_bf16 v[90:93], v[152:155], v[192:195], v[90:93]
	v_mfma_f32_16x16x32_bf16 v[78:81], v[142:145], v[200:203], v[78:81]
	v_mfma_f32_16x16x32_bf16 v[74:77], v[152:155], v[200:203], v[74:77]
	v_mfma_f32_16x16x32_bf16 v[118:121], v[156:159], v[172:175], v[118:121]
	v_mfma_f32_16x16x32_bf16 v[114:117], v[164:167], v[172:175], v[114:117]
	v_mfma_f32_16x16x32_bf16 v[102:105], v[156:159], v[180:183], v[102:105]
	v_mfma_f32_16x16x32_bf16 v[98:101], v[164:167], v[180:183], v[98:101]
	v_mfma_f32_16x16x32_bf16 v[86:89], v[156:159], v[188:191], v[86:89]
	v_mfma_f32_16x16x32_bf16 v[82:85], v[164:167], v[188:191], v[82:85]
	v_mfma_f32_16x16x32_bf16 v[70:73], v[156:159], v[196:199], v[70:73]
	v_mfma_f32_16x16x32_bf16 v[66:69], v[164:167], v[196:199], v[66:69]
	v_mfma_f32_16x16x32_bf16 v[118:121], v[160:163], v[176:179], v[118:121]
	v_mfma_f32_16x16x32_bf16 v[114:117], v[168:171], v[176:179], v[114:117]
	v_mfma_f32_16x16x32_bf16 v[102:105], v[160:163], v[184:187], v[102:105]
	v_mfma_f32_16x16x32_bf16 v[98:101], v[168:171], v[184:187], v[98:101]
	v_mfma_f32_16x16x32_bf16 v[86:89], v[160:163], v[192:195], v[86:89]
	v_mfma_f32_16x16x32_bf16 v[82:85], v[168:171], v[192:195], v[82:85]
	v_mfma_f32_16x16x32_bf16 v[70:73], v[160:163], v[200:203], v[70:73]
	v_mfma_f32_16x16x32_bf16 v[66:69], v[168:171], v[200:203], v[66:69]
	s_barrier
	s_setprio 0
	ds_read_b128 v[172:175], v133 offset:49152
	ds_read_b128 v[176:179], v133 offset:50176
	s_add_i32 s59, s58, 0x80
	s_mov_b32 m0, s40
	s_nop 0
	buffer_load_dwordx4 v130, s[8:11], s59 offen lds
	ds_read_b128 v[180:183], v133 offset:51200
	ds_read_b128 v[184:187], v133 offset:52224
	s_add_i32 s58, s58, 0xb0080
	s_mov_b32 m0, s41
	s_nop 0
	buffer_load_dwordx4 v131, s[8:11], s59 offen lds
	ds_read_b128 v[188:191], v133 offset:53248
	ds_read_b128 v[192:195], v133 offset:54272
	s_nop 0
	s_mov_b32 m0, s44
	s_nop 0
	buffer_load_dwordx4 v130, s[8:11], s58 offen lds
	ds_read_b128 v[196:199], v133 offset:55296
	ds_read_b128 v[200:203], v133 offset:56320
	s_nop 0
	s_mov_b32 m0, s45
	s_nop 0
	buffer_load_dwordx4 v131, s[8:11], s58 offen lds
	s_nop 0
	s_mov_b32 m0, s42
	s_nop 0
	buffer_load_dwordx4 v130, s[12:15], s55 offen lds
	s_nop 0
	s_mov_b32 m0, s43
	s_nop 0
	buffer_load_dwordx4 v131, s[12:15], s55 offen lds
	s_waitcnt vmcnt(8)
	s_waitcnt lgkmcnt(0)
	s_setprio 1
	s_barrier
	v_mfma_f32_16x16x32_bf16 v[62:65], v[138:141], v[172:175], v[62:65]
	v_mfma_f32_16x16x32_bf16 v[58:61], v[148:151], v[172:175], v[58:61]
	v_mfma_f32_16x16x32_bf16 v[46:49], v[138:141], v[180:183], v[46:49]
	v_mfma_f32_16x16x32_bf16 v[42:45], v[148:151], v[180:183], v[42:45]
	v_mfma_f32_16x16x32_bf16 v[30:33], v[138:141], v[188:191], v[30:33]
	v_mfma_f32_16x16x32_bf16 v[26:29], v[148:151], v[188:191], v[26:29]
	v_mfma_f32_16x16x32_bf16 v[14:17], v[138:141], v[196:199], v[14:17]
	v_mfma_f32_16x16x32_bf16 v[10:13], v[148:151], v[196:199], v[10:13]
	v_mfma_f32_16x16x32_bf16 v[62:65], v[142:145], v[176:179], v[62:65]
	v_mfma_f32_16x16x32_bf16 v[58:61], v[152:155], v[176:179], v[58:61]
	v_mfma_f32_16x16x32_bf16 v[46:49], v[142:145], v[184:187], v[46:49]
	v_mfma_f32_16x16x32_bf16 v[42:45], v[152:155], v[184:187], v[42:45]
	v_mfma_f32_16x16x32_bf16 v[30:33], v[142:145], v[192:195], v[30:33]
	v_mfma_f32_16x16x32_bf16 v[26:29], v[152:155], v[192:195], v[26:29]
	v_mfma_f32_16x16x32_bf16 v[14:17], v[142:145], v[200:203], v[14:17]
	v_mfma_f32_16x16x32_bf16 v[10:13], v[152:155], v[200:203], v[10:13]
	v_mfma_f32_16x16x32_bf16 v[54:57], v[156:159], v[172:175], v[54:57]
	v_mfma_f32_16x16x32_bf16 v[50:53], v[164:167], v[172:175], v[50:53]
	v_mfma_f32_16x16x32_bf16 v[38:41], v[156:159], v[180:183], v[38:41]
	v_mfma_f32_16x16x32_bf16 v[34:37], v[164:167], v[180:183], v[34:37]
	v_mfma_f32_16x16x32_bf16 v[22:25], v[156:159], v[188:191], v[22:25]
	v_mfma_f32_16x16x32_bf16 v[18:21], v[164:167], v[188:191], v[18:21]
	v_mfma_f32_16x16x32_bf16 v[6:9], v[156:159], v[196:199], v[6:9]
	v_mfma_f32_16x16x32_bf16 v[2:5], v[164:167], v[196:199], v[2:5]
	v_mfma_f32_16x16x32_bf16 v[54:57], v[160:163], v[176:179], v[54:57]
	v_mfma_f32_16x16x32_bf16 v[50:53], v[168:171], v[176:179], v[50:53]
	v_mfma_f32_16x16x32_bf16 v[38:41], v[160:163], v[184:187], v[38:41]
	v_mfma_f32_16x16x32_bf16 v[34:37], v[168:171], v[184:187], v[34:37]
	v_mfma_f32_16x16x32_bf16 v[22:25], v[160:163], v[192:195], v[22:25]
	v_mfma_f32_16x16x32_bf16 v[18:21], v[168:171], v[192:195], v[18:21]
	v_mfma_f32_16x16x32_bf16 v[6:9], v[160:163], v[200:203], v[6:9]
	v_mfma_f32_16x16x32_bf16 v[2:5], v[168:171], v[200:203], v[2:5]
	s_barrier
	s_setprio 0
	s_add_i32 s0, s0, 2
	s_addk_i32 s1, 0x100
	s_cmp_gt_u32 s0, 41
	s_cbranch_scc0 .LBB0_467
	s_andn2_b64 vcc, exec, s[6:7]
	s_cbranch_vccnz .LBB0_455
	v_mov_b32_e32 v2, 0
	s_mov_b32 s18, s50
	s_mov_b32 s31, s51
	s_mov_b32 s33, s54
	s_mov_b32 s3, s53
	s_mov_b32 s49, s52
	v_mov_b32_e32 v3, v2
	v_mov_b32_e32 v4, v2
	v_mov_b32_e32 v5, v2
	v_mov_b32_e32 v6, v2
	v_mov_b32_e32 v7, v2
	v_mov_b32_e32 v8, v2
	v_mov_b32_e32 v9, v2
	v_mov_b32_e32 v18, v2
	v_mov_b32_e32 v19, v2
	v_mov_b32_e32 v20, v2
	v_mov_b32_e32 v21, v2
	v_mov_b32_e32 v22, v2
	v_mov_b32_e32 v23, v2
	v_mov_b32_e32 v24, v2
	v_mov_b32_e32 v25, v2
	v_mov_b32_e32 v34, v2
	v_mov_b32_e32 v35, v2
	v_mov_b32_e32 v36, v2
	v_mov_b32_e32 v37, v2
	v_mov_b32_e32 v38, v2
	v_mov_b32_e32 v39, v2
	v_mov_b32_e32 v40, v2
	v_mov_b32_e32 v41, v2
	v_mov_b32_e32 v50, v2
	v_mov_b32_e32 v51, v2
	v_mov_b32_e32 v52, v2
	v_mov_b32_e32 v53, v2
	v_mov_b32_e32 v54, v2
	v_mov_b32_e32 v55, v2
	v_mov_b32_e32 v56, v2
	v_mov_b32_e32 v57, v2
	v_mov_b32_e32 v10, v2
	v_mov_b32_e32 v11, v2
	v_mov_b32_e32 v12, v2
	v_mov_b32_e32 v13, v2
	v_mov_b32_e32 v14, v2
	v_mov_b32_e32 v15, v2
	v_mov_b32_e32 v16, v2
	v_mov_b32_e32 v17, v2
	v_mov_b32_e32 v26, v2
	v_mov_b32_e32 v27, v2
	v_mov_b32_e32 v28, v2
	v_mov_b32_e32 v29, v2
	v_mov_b32_e32 v30, v2
	v_mov_b32_e32 v31, v2
	v_mov_b32_e32 v32, v2
	v_mov_b32_e32 v33, v2
	v_mov_b32_e32 v42, v2
	v_mov_b32_e32 v43, v2
	v_mov_b32_e32 v44, v2
	v_mov_b32_e32 v45, v2
	v_mov_b32_e32 v46, v2
	v_mov_b32_e32 v47, v2
	v_mov_b32_e32 v48, v2
	v_mov_b32_e32 v49, v2
	v_mov_b32_e32 v58, v2
	v_mov_b32_e32 v59, v2
	v_mov_b32_e32 v60, v2
	v_mov_b32_e32 v61, v2
	v_mov_b32_e32 v62, v2
	v_mov_b32_e32 v63, v2
	v_mov_b32_e32 v64, v2
	v_mov_b32_e32 v65, v2
	v_mov_b32_e32 v66, v2
	v_mov_b32_e32 v67, v2
	v_mov_b32_e32 v68, v2
	v_mov_b32_e32 v69, v2
	v_mov_b32_e32 v70, v2
	v_mov_b32_e32 v71, v2
	v_mov_b32_e32 v72, v2
	v_mov_b32_e32 v73, v2
	v_mov_b32_e32 v82, v2
	v_mov_b32_e32 v83, v2
	v_mov_b32_e32 v84, v2
	v_mov_b32_e32 v85, v2
	v_mov_b32_e32 v86, v2
	v_mov_b32_e32 v87, v2
	v_mov_b32_e32 v88, v2
	v_mov_b32_e32 v89, v2
	v_mov_b32_e32 v98, v2
	v_mov_b32_e32 v99, v2
	v_mov_b32_e32 v100, v2
	v_mov_b32_e32 v101, v2
	v_mov_b32_e32 v102, v2
	v_mov_b32_e32 v103, v2
	v_mov_b32_e32 v104, v2
	v_mov_b32_e32 v105, v2
	v_mov_b32_e32 v114, v2
	v_mov_b32_e32 v115, v2
	v_mov_b32_e32 v116, v2
	v_mov_b32_e32 v117, v2
	v_mov_b32_e32 v118, v2
	v_mov_b32_e32 v119, v2
	v_mov_b32_e32 v120, v2
	v_mov_b32_e32 v121, v2
	v_mov_b32_e32 v74, v2
	v_mov_b32_e32 v75, v2
	v_mov_b32_e32 v76, v2
	v_mov_b32_e32 v77, v2
	v_mov_b32_e32 v78, v2
	v_mov_b32_e32 v79, v2
	v_mov_b32_e32 v80, v2
	v_mov_b32_e32 v81, v2
	v_mov_b32_e32 v90, v2
	v_mov_b32_e32 v91, v2
	v_mov_b32_e32 v92, v2
	v_mov_b32_e32 v93, v2
	v_mov_b32_e32 v94, v2
	v_mov_b32_e32 v95, v2
	v_mov_b32_e32 v96, v2
	v_mov_b32_e32 v97, v2
	v_mov_b32_e32 v106, v2
	v_mov_b32_e32 v107, v2
	v_mov_b32_e32 v108, v2
	v_mov_b32_e32 v109, v2
	v_mov_b32_e32 v110, v2
	v_mov_b32_e32 v111, v2
	v_mov_b32_e32 v112, v2
	v_mov_b32_e32 v113, v2
	v_mov_b32_e32 v122, v2
	v_mov_b32_e32 v123, v2
	v_mov_b32_e32 v124, v2
	v_mov_b32_e32 v125, v2
	v_mov_b32_e32 v134, v2
	v_mov_b32_e32 v135, v2
	v_mov_b32_e32 v136, v2
	v_mov_b32_e32 v137, v2
	s_branch .LBB0_455

.LBB0_619:
	ds_read_b128 v[38:41], v210
	ds_read_b128 v[42:45], v210 offset:1024
	ds_read_b128 v[46:49], v210 offset:2048
	ds_read_b128 v[58:61], v210 offset:3072
	ds_read_b128 v[142:145], v211
	ds_read_b128 v[146:149], v211 offset:1024
	ds_read_b128 v[150:153], v211 offset:2048
	ds_read_b128 v[154:157], v211 offset:3072
	s_add_i32 s6, s1, 0xfffe0080
	s_cmp_eq_u32 s3, 4
	s_cselect_b32 s8, s75, s6
	s_cselect_b32 s7, s0, s2
	s_add_i32 s6, s8, 0x80
	s_mov_b32 m0, s68
	s_nop 0
	buffer_load_dwordx4 v206, s[16:19], s1 offen lds
	s_nop 0
	s_mov_b32 m0, s69
	s_nop 0
	buffer_load_dwordx4 v207, s[16:19], s1 offen lds
	ds_read_b128 v[166:169], v212
	ds_read_b128 v[170:173], v212 offset:1024
	ds_read_b128 v[174:177], v212 offset:2048
	ds_read_b128 v[178:181], v212 offset:3072
	ds_read_b128 v[190:193], v212 offset:4096
	ds_read_b128 v[194:197], v212 offset:5120
	ds_read_b128 v[198:201], v212 offset:6144
	ds_read_b128 v[216:219], v212 offset:7168
	s_waitcnt vmcnt(8)
	s_waitcnt lgkmcnt(0)
	s_setprio 1
	s_barrier
	v_mfma_i32_16x16x64_i8 v[162:165], v[38:41], v[166:169], v[162:165]
	v_mfma_i32_16x16x64_i8 v[158:161], v[46:49], v[166:169], v[158:161]
	v_mfma_i32_16x16x64_i8 v[130:133], v[38:41], v[174:177], v[130:133]
	v_mfma_i32_16x16x64_i8 v[126:129], v[46:49], v[174:177], v[126:129]
	v_mfma_i32_16x16x64_i8 v[114:117], v[38:41], v[190:193], v[114:117]
	v_mfma_i32_16x16x64_i8 v[110:113], v[46:49], v[190:193], v[110:113]
	v_mfma_i32_16x16x64_i8 v[98:101], v[38:41], v[198:201], v[98:101]
	v_mfma_i32_16x16x64_i8 v[94:97], v[46:49], v[198:201], v[94:97]
	v_mfma_i32_16x16x64_i8 v[162:165], v[42:45], v[170:173], v[162:165]
	v_mfma_i32_16x16x64_i8 v[158:161], v[58:61], v[170:173], v[158:161]
	v_mfma_i32_16x16x64_i8 v[130:133], v[42:45], v[178:181], v[130:133]
	v_mfma_i32_16x16x64_i8 v[126:129], v[58:61], v[178:181], v[126:129]
	v_mfma_i32_16x16x64_i8 v[114:117], v[42:45], v[194:197], v[114:117]
	v_mfma_i32_16x16x64_i8 v[110:113], v[58:61], v[194:197], v[110:113]
	v_mfma_i32_16x16x64_i8 v[98:101], v[42:45], v[216:219], v[98:101]
	v_mfma_i32_16x16x64_i8 v[94:97], v[58:61], v[216:219], v[94:97]
	v_mfma_i32_16x16x64_i8 v[138:141], v[142:145], v[166:169], v[138:141]
	v_mfma_i32_16x16x64_i8 v[134:137], v[150:153], v[166:169], v[134:137]
	v_mfma_i32_16x16x64_i8 v[122:125], v[142:145], v[174:177], v[122:125]
	v_mfma_i32_16x16x64_i8 v[118:121], v[150:153], v[174:177], v[118:121]
	v_mfma_i32_16x16x64_i8 v[106:109], v[142:145], v[190:193], v[106:109]
	v_mfma_i32_16x16x64_i8 v[102:105], v[150:153], v[190:193], v[102:105]
	v_mfma_i32_16x16x64_i8 v[90:93], v[142:145], v[198:201], v[90:93]
	v_mfma_i32_16x16x64_i8 v[86:89], v[150:153], v[198:201], v[86:89]
	v_mfma_i32_16x16x64_i8 v[138:141], v[146:149], v[170:173], v[138:141]
	v_mfma_i32_16x16x64_i8 v[134:137], v[154:157], v[170:173], v[134:137]
	v_mfma_i32_16x16x64_i8 v[122:125], v[146:149], v[178:181], v[122:125]
	v_mfma_i32_16x16x64_i8 v[118:121], v[154:157], v[178:181], v[118:121]
	v_mfma_i32_16x16x64_i8 v[106:109], v[146:149], v[194:197], v[106:109]
	v_mfma_i32_16x16x64_i8 v[102:105], v[154:157], v[194:197], v[102:105]
	v_mfma_i32_16x16x64_i8 v[90:93], v[146:149], v[216:219], v[90:93]
	v_mfma_i32_16x16x64_i8 v[86:89], v[154:157], v[216:219], v[86:89]
	s_barrier
	s_setprio 0
	ds_read_b128 v[166:169], v212 offset:16384
	ds_read_b128 v[170:173], v212 offset:17408
	s_mov_b32 m0, s48
	s_nop 0
	buffer_load_dwordx4 v204, s[12:15], s7 offen lds
	ds_read_b128 v[174:177], v212 offset:18432
	ds_read_b128 v[178:181], v212 offset:19456
	s_add_i32 s9, s7, 0x20000
	s_mov_b32 m0, s49
	s_nop 0
	buffer_load_dwordx4 v205, s[12:15], s7 offen lds
	ds_read_b128 v[190:193], v212 offset:20480
	ds_read_b128 v[194:197], v212 offset:21504
	s_nop 0
	s_mov_b32 m0, s50
	s_nop 0
	buffer_load_dwordx4 v204, s[12:15], s9 offen lds
	ds_read_b128 v[198:201], v212 offset:22528
	ds_read_b128 v[216:219], v212 offset:23552
	s_nop 0
	s_mov_b32 m0, s51
	s_nop 0
	buffer_load_dwordx4 v205, s[12:15], s9 offen lds
	s_nop 0
	s_mov_b32 m0, s47
	s_nop 0
	buffer_load_dwordx4 v206, s[16:19], s8 offen lds
	s_nop 0
	s_mov_b32 m0, s52
	s_nop 0
	buffer_load_dwordx4 v207, s[16:19], s8 offen lds
	s_waitcnt vmcnt(8)
	s_waitcnt lgkmcnt(0)
	s_setprio 1
	s_barrier
	v_mfma_i32_16x16x64_i8 v[82:85], v[38:41], v[166:169], v[82:85]
	v_mfma_i32_16x16x64_i8 v[78:81], v[46:49], v[166:169], v[78:81]
	v_mfma_i32_16x16x64_i8 v[66:69], v[38:41], v[174:177], v[66:69]
	v_mfma_i32_16x16x64_i8 v[62:65], v[46:49], v[174:177], v[62:65]
	v_mfma_i32_16x16x64_i8 v[34:37], v[38:41], v[190:193], v[34:37]
	v_mfma_i32_16x16x64_i8 v[30:33], v[46:49], v[190:193], v[30:33]
	v_mfma_i32_16x16x64_i8 v[18:21], v[38:41], v[198:201], v[18:21]
	v_mfma_i32_16x16x64_i8 v[14:17], v[46:49], v[198:201], v[14:17]
	v_mfma_i32_16x16x64_i8 v[82:85], v[42:45], v[170:173], v[82:85]
	v_mfma_i32_16x16x64_i8 v[78:81], v[58:61], v[170:173], v[78:81]
	v_mfma_i32_16x16x64_i8 v[66:69], v[42:45], v[178:181], v[66:69]
	v_mfma_i32_16x16x64_i8 v[62:65], v[58:61], v[178:181], v[62:65]
	v_mfma_i32_16x16x64_i8 v[34:37], v[42:45], v[194:197], v[34:37]
	v_mfma_i32_16x16x64_i8 v[30:33], v[58:61], v[194:197], v[30:33]
	v_mfma_i32_16x16x64_i8 v[18:21], v[42:45], v[216:219], v[18:21]
	v_mfma_i32_16x16x64_i8 v[14:17], v[58:61], v[216:219], v[14:17]
	v_mfma_i32_16x16x64_i8 v[50:53], v[150:153], v[174:177], v[50:53]
	v_mfma_i32_16x16x64_i8 v[26:29], v[142:145], v[190:193], v[26:29]
	v_mfma_i32_16x16x64_i8 v[22:25], v[150:153], v[190:193], v[22:25]
	v_mfma_i32_16x16x64_i8 v[10:13], v[142:145], v[198:201], v[10:13]
	v_mfma_i32_16x16x64_i8 v[4:7], v[150:153], v[198:201], v[6:9]
	v_mfma_i32_16x16x64_i8 v[38:41], v[142:145], v[166:169], v[74:77]
	v_mfma_i32_16x16x64_i8 v[42:45], v[150:153], v[166:169], v[70:73]
	v_mfma_i32_16x16x64_i8 v[46:49], v[142:145], v[174:177], v[54:57]
	v_mfma_i32_16x16x64_i8 v[50:53], v[154:157], v[178:181], v[50:53]
	v_mfma_i32_16x16x64_i8 v[26:29], v[146:149], v[194:197], v[26:29]
	v_mfma_i32_16x16x64_i8 v[22:25], v[154:157], v[194:197], v[22:25]
	v_mfma_i32_16x16x64_i8 v[10:13], v[146:149], v[216:219], v[10:13]
	v_mfma_i32_16x16x64_i8 v[4:7], v[154:157], v[216:219], v[4:7]
	v_mfma_i32_16x16x64_i8 v[38:41], v[146:149], v[170:173], v[38:41]
	v_mfma_i32_16x16x64_i8 v[42:45], v[154:157], v[170:173], v[42:45]
	v_mfma_i32_16x16x64_i8 v[46:49], v[146:149], v[178:181], v[46:49]
	s_barrier
	s_setprio 0
	ds_read_b128 v[54:57], v213
	ds_read_b128 v[58:61], v213 offset:1024
	ds_read_b128 v[70:73], v213 offset:2048
	ds_read_b128 v[74:77], v213 offset:3072
	ds_read_b128 v[142:145], v214
	ds_read_b128 v[146:149], v214 offset:1024
	ds_read_b128 v[150:153], v214 offset:2048
	ds_read_b128 v[154:157], v214 offset:3072
	s_add_i32 s8, s8, 0x20000
	s_mov_b32 m0, s53
	s_nop 0
	buffer_load_dwordx4 v206, s[16:19], s8 offen lds
	s_nop 0
	s_mov_b32 m0, s54
	s_nop 0
	buffer_load_dwordx4 v207, s[16:19], s8 offen lds
	ds_read_b128 v[166:169], v212 offset:32768
	ds_read_b128 v[170:173], v212 offset:33792
	ds_read_b128 v[174:177], v212 offset:34816
	ds_read_b128 v[178:181], v212 offset:35840
	ds_read_b128 v[190:193], v212 offset:36864
	ds_read_b128 v[194:197], v212 offset:37888
	ds_read_b128 v[198:201], v212 offset:38912
	ds_read_b128 v[216:219], v212 offset:39936
	s_waitcnt vmcnt(8)
	s_waitcnt lgkmcnt(0)
	s_setprio 1
	s_barrier
	v_mfma_i32_16x16x64_i8 v[162:165], v[54:57], v[166:169], v[162:165]
	v_mfma_i32_16x16x64_i8 v[158:161], v[70:73], v[166:169], v[158:161]
	v_mfma_i32_16x16x64_i8 v[130:133], v[54:57], v[174:177], v[130:133]
	v_mfma_i32_16x16x64_i8 v[126:129], v[70:73], v[174:177], v[126:129]
	v_mfma_i32_16x16x64_i8 v[114:117], v[54:57], v[190:193], v[114:117]
	v_mfma_i32_16x16x64_i8 v[110:113], v[70:73], v[190:193], v[110:113]
	v_mfma_i32_16x16x64_i8 v[98:101], v[54:57], v[198:201], v[98:101]
	v_mfma_i32_16x16x64_i8 v[94:97], v[70:73], v[198:201], v[94:97]
	v_mfma_i32_16x16x64_i8 v[162:165], v[58:61], v[170:173], v[162:165]
	v_mfma_i32_16x16x64_i8 v[158:161], v[74:77], v[170:173], v[158:161]
	v_mfma_i32_16x16x64_i8 v[130:133], v[58:61], v[178:181], v[130:133]
	v_mfma_i32_16x16x64_i8 v[126:129], v[74:77], v[178:181], v[126:129]
	v_mfma_i32_16x16x64_i8 v[114:117], v[58:61], v[194:197], v[114:117]
	v_mfma_i32_16x16x64_i8 v[110:113], v[74:77], v[194:197], v[110:113]
	v_mfma_i32_16x16x64_i8 v[98:101], v[58:61], v[216:219], v[98:101]
	v_mfma_i32_16x16x64_i8 v[94:97], v[74:77], v[216:219], v[94:97]
	v_mfma_i32_16x16x64_i8 v[138:141], v[142:145], v[166:169], v[138:141]
	v_mfma_i32_16x16x64_i8 v[134:137], v[150:153], v[166:169], v[134:137]
	v_mfma_i32_16x16x64_i8 v[122:125], v[142:145], v[174:177], v[122:125]
	v_mfma_i32_16x16x64_i8 v[118:121], v[150:153], v[174:177], v[118:121]
	v_mfma_i32_16x16x64_i8 v[106:109], v[142:145], v[190:193], v[106:109]
	v_mfma_i32_16x16x64_i8 v[102:105], v[150:153], v[190:193], v[102:105]
	v_mfma_i32_16x16x64_i8 v[90:93], v[142:145], v[198:201], v[90:93]
	v_mfma_i32_16x16x64_i8 v[86:89], v[150:153], v[198:201], v[86:89]
	v_mfma_i32_16x16x64_i8 v[138:141], v[146:149], v[170:173], v[138:141]
	v_mfma_i32_16x16x64_i8 v[134:137], v[154:157], v[170:173], v[134:137]
	v_mfma_i32_16x16x64_i8 v[122:125], v[146:149], v[178:181], v[122:125]
	v_mfma_i32_16x16x64_i8 v[118:121], v[154:157], v[178:181], v[118:121]
	v_mfma_i32_16x16x64_i8 v[106:109], v[146:149], v[194:197], v[106:109]
	v_mfma_i32_16x16x64_i8 v[102:105], v[154:157], v[194:197], v[102:105]
	v_mfma_i32_16x16x64_i8 v[90:93], v[146:149], v[216:219], v[90:93]
	v_mfma_i32_16x16x64_i8 v[86:89], v[154:157], v[216:219], v[86:89]
	s_barrier
	s_setprio 0
	ds_read_b128 v[166:169], v212 offset:49152
	ds_read_b128 v[170:173], v212 offset:50176
	s_or_b32 s8, s7, 0x80
	s_mov_b32 m0, s62
	s_nop 0
	buffer_load_dwordx4 v204, s[12:15], s8 offen lds
	ds_read_b128 v[174:177], v212 offset:51200
	ds_read_b128 v[178:181], v212 offset:52224
	s_add_i32 s7, s7, 0x20080
	s_mov_b32 m0, s63
	s_nop 0
	buffer_load_dwordx4 v205, s[12:15], s8 offen lds
	ds_read_b128 v[190:193], v212 offset:53248
	ds_read_b128 v[194:197], v212 offset:54272
	s_nop 0
	s_mov_b32 m0, s66
	s_nop 0
	buffer_load_dwordx4 v204, s[12:15], s7 offen lds
	ds_read_b128 v[198:201], v212 offset:55296
	ds_read_b128 v[216:219], v212 offset:56320
	s_nop 0
	s_mov_b32 m0, s67
	s_nop 0
	buffer_load_dwordx4 v205, s[12:15], s7 offen lds
	s_nop 0
	s_mov_b32 m0, s64
	s_nop 0
	buffer_load_dwordx4 v206, s[16:19], s6 offen lds
	s_nop 0
	s_mov_b32 m0, s65
	s_nop 0
	buffer_load_dwordx4 v207, s[16:19], s6 offen lds
	s_waitcnt vmcnt(8)
	s_waitcnt lgkmcnt(0)
	s_setprio 1
	s_barrier
	v_mfma_i32_16x16x64_i8 v[82:85], v[54:57], v[166:169], v[82:85]
	v_mfma_i32_16x16x64_i8 v[78:81], v[70:73], v[166:169], v[78:81]
	v_mfma_i32_16x16x64_i8 v[66:69], v[54:57], v[174:177], v[66:69]
	v_mfma_i32_16x16x64_i8 v[62:65], v[70:73], v[174:177], v[62:65]
	v_mfma_i32_16x16x64_i8 v[34:37], v[54:57], v[190:193], v[34:37]
	v_mfma_i32_16x16x64_i8 v[30:33], v[70:73], v[190:193], v[30:33]
	v_mfma_i32_16x16x64_i8 v[18:21], v[54:57], v[198:201], v[18:21]
	v_mfma_i32_16x16x64_i8 v[14:17], v[70:73], v[198:201], v[14:17]
	v_mfma_i32_16x16x64_i8 v[82:85], v[58:61], v[170:173], v[82:85]
	v_mfma_i32_16x16x64_i8 v[78:81], v[74:77], v[170:173], v[78:81]
	v_mfma_i32_16x16x64_i8 v[66:69], v[58:61], v[178:181], v[66:69]
	v_mfma_i32_16x16x64_i8 v[62:65], v[74:77], v[178:181], v[62:65]
	v_mfma_i32_16x16x64_i8 v[34:37], v[58:61], v[194:197], v[34:37]
	v_mfma_i32_16x16x64_i8 v[30:33], v[74:77], v[194:197], v[30:33]
	v_mfma_i32_16x16x64_i8 v[18:21], v[58:61], v[216:219], v[18:21]
	v_mfma_i32_16x16x64_i8 v[14:17], v[74:77], v[216:219], v[14:17]
	v_mfma_i32_16x16x64_i8 v[38:41], v[142:145], v[166:169], v[38:41]
	v_mfma_i32_16x16x64_i8 v[74:77], v[146:149], v[170:173], v[38:41]
	v_mfma_i32_16x16x64_i8 v[38:41], v[150:153], v[166:169], v[42:45]
	v_mfma_i32_16x16x64_i8 v[70:73], v[154:157], v[170:173], v[38:41]
	v_mfma_i32_16x16x64_i8 v[38:41], v[142:145], v[174:177], v[46:49]
	v_mfma_i32_16x16x64_i8 v[54:57], v[146:149], v[178:181], v[38:41]
	v_mfma_i32_16x16x64_i8 v[38:41], v[150:153], v[174:177], v[50:53]
	v_mfma_i32_16x16x64_i8 v[26:29], v[142:145], v[190:193], v[26:29]
	v_mfma_i32_16x16x64_i8 v[22:25], v[150:153], v[190:193], v[22:25]
	v_mfma_i32_16x16x64_i8 v[8:11], v[142:145], v[198:201], v[10:13]
	v_mfma_i32_16x16x64_i8 v[4:7], v[150:153], v[198:201], v[4:7]
	v_mfma_i32_16x16x64_i8 v[50:53], v[154:157], v[178:181], v[38:41]
	v_mfma_i32_16x16x64_i8 v[26:29], v[146:149], v[194:197], v[26:29]
	v_mfma_i32_16x16x64_i8 v[22:25], v[154:157], v[194:197], v[22:25]
	v_mfma_i32_16x16x64_i8 v[10:13], v[146:149], v[216:219], v[8:11]
	v_mfma_i32_16x16x64_i8 v[6:9], v[154:157], v[216:219], v[4:7]
	s_barrier
	s_setprio 0
	s_add_i32 s3, s3, 2
	s_addk_i32 s1, 0x100
	s_addk_i32 s2, 0x100
	s_cmp_gt_u32 s3, 5
	s_cbranch_scc0 .LBB0_619
	s_and_b64 vcc, exec, s[34:35]
	s_cbranch_vccz .LBB0_622
	s_barrier

.LBB0_943:
	v_add_u32_e32 v150, 0x10000, v8
	v_add_u32_e32 v166, 0x14000, v8
	ds_read_b128 v[10:13], v150
	ds_read_b128 v[14:17], v150 offset:1024
	ds_read_b128 v[146:149], v150 offset:2048
	ds_read_b128 v[150:153], v150 offset:3072
	ds_read_b128 v[154:157], v166
	ds_read_b128 v[158:161], v166 offset:1024
	ds_read_b128 v[162:165], v166 offset:2048
	ds_read_b128 v[166:169], v166 offset:3072
	s_add_i32 s61, s37, s58
	s_add_i32 s60, s33, s58
	s_add_i32 s59, s61, 0x400
	s_addk_i32 s60, 0x400
	s_cmp_eq_u32 s58, 0
	s_cselect_b32 s62, s53, s59
	s_cselect_b32 s60, s54, s60
	s_or_b32 s59, s62, 0x80
	s_add_i32 s61, s61, 0x20380
	s_mov_b32 m0, s48
	s_nop 0
	buffer_load_dwordx4 v6, s[12:15], s61 offen lds
	s_nop 0
	s_mov_b32 m0, s49
	s_nop 0
	buffer_load_dwordx4 v7, s[12:15], s61 offen lds
	ds_read_b128 v[170:173], v9
	ds_read_b128 v[174:177], v9 offset:1024
	ds_read_b128 v[178:181], v9 offset:2048
	ds_read_b128 v[182:185], v9 offset:3072
	ds_read_b128 v[186:189], v9 offset:4096
	ds_read_b128 v[190:193], v9 offset:5120
	ds_read_b128 v[194:197], v9 offset:6144
	ds_read_b128 v[198:201], v9 offset:7168
	s_waitcnt vmcnt(8)
	s_waitcnt lgkmcnt(0)
	s_setprio 1
	s_barrier
	v_mfma_i32_16x16x64_i8 v[142:145], v[10:13], v[170:173], v[142:145]
	v_mfma_i32_16x16x64_i8 v[138:141], v[146:149], v[170:173], v[138:141]
	v_mfma_i32_16x16x64_i8 v[126:129], v[10:13], v[178:181], v[126:129]
	v_mfma_i32_16x16x64_i8 v[122:125], v[146:149], v[178:181], v[122:125]
	v_mfma_i32_16x16x64_i8 v[110:113], v[10:13], v[186:189], v[110:113]
	v_mfma_i32_16x16x64_i8 v[106:109], v[146:149], v[186:189], v[106:109]
	v_mfma_i32_16x16x64_i8 v[94:97], v[10:13], v[194:197], v[94:97]
	v_mfma_i32_16x16x64_i8 v[90:93], v[146:149], v[194:197], v[90:93]
	v_mfma_i32_16x16x64_i8 v[142:145], v[14:17], v[174:177], v[142:145]
	v_mfma_i32_16x16x64_i8 v[138:141], v[150:153], v[174:177], v[138:141]
	v_mfma_i32_16x16x64_i8 v[126:129], v[14:17], v[182:185], v[126:129]
	v_mfma_i32_16x16x64_i8 v[122:125], v[150:153], v[182:185], v[122:125]
	v_mfma_i32_16x16x64_i8 v[110:113], v[14:17], v[190:193], v[110:113]
	v_mfma_i32_16x16x64_i8 v[106:109], v[150:153], v[190:193], v[106:109]
	v_mfma_i32_16x16x64_i8 v[94:97], v[14:17], v[198:201], v[94:97]
	v_mfma_i32_16x16x64_i8 v[90:93], v[150:153], v[198:201], v[90:93]
	v_mfma_i32_16x16x64_i8 v[134:137], v[154:157], v[170:173], v[134:137]
	v_mfma_i32_16x16x64_i8 v[130:133], v[162:165], v[170:173], v[130:133]
	v_mfma_i32_16x16x64_i8 v[118:121], v[154:157], v[178:181], v[118:121]
	v_mfma_i32_16x16x64_i8 v[114:117], v[162:165], v[178:181], v[114:117]
	v_mfma_i32_16x16x64_i8 v[102:105], v[154:157], v[186:189], v[102:105]
	v_mfma_i32_16x16x64_i8 v[98:101], v[162:165], v[186:189], v[98:101]
	v_mfma_i32_16x16x64_i8 v[86:89], v[154:157], v[194:197], v[86:89]
	v_mfma_i32_16x16x64_i8 v[82:85], v[162:165], v[194:197], v[82:85]
	v_mfma_i32_16x16x64_i8 v[134:137], v[158:161], v[174:177], v[134:137]
	v_mfma_i32_16x16x64_i8 v[130:133], v[166:169], v[174:177], v[130:133]
	v_mfma_i32_16x16x64_i8 v[118:121], v[158:161], v[182:185], v[118:121]
	v_mfma_i32_16x16x64_i8 v[114:117], v[166:169], v[182:185], v[114:117]
	v_mfma_i32_16x16x64_i8 v[102:105], v[158:161], v[190:193], v[102:105]
	v_mfma_i32_16x16x64_i8 v[98:101], v[166:169], v[190:193], v[98:101]
	v_mfma_i32_16x16x64_i8 v[86:89], v[158:161], v[198:201], v[86:89]
	v_mfma_i32_16x16x64_i8 v[82:85], v[166:169], v[198:201], v[82:85]
	s_barrier
	s_setprio 0
	ds_read_b128 v[170:173], v9 offset:16384
	ds_read_b128 v[174:177], v9 offset:17408
	s_mov_b32 m0, s29
	s_nop 0
	buffer_load_dwordx4 v6, s[8:11], s60 offen lds
	ds_read_b128 v[178:181], v9 offset:18432
	ds_read_b128 v[182:185], v9 offset:19456
	s_add_i32 s61, s60, 0x20000
	s_mov_b32 m0, s34
	s_nop 0
	buffer_load_dwordx4 v7, s[8:11], s60 offen lds
	ds_read_b128 v[186:189], v9 offset:20480
	ds_read_b128 v[190:193], v9 offset:21504
	s_nop 0
	s_mov_b32 m0, s35
	s_nop 0
	buffer_load_dwordx4 v6, s[8:11], s61 offen lds
	ds_read_b128 v[194:197], v9 offset:22528
	ds_read_b128 v[198:201], v9 offset:23552
	s_nop 0
	s_mov_b32 m0, s36
	s_nop 0
	buffer_load_dwordx4 v7, s[8:11], s61 offen lds
	s_nop 0
	s_mov_b32 m0, s28
	s_nop 0
	buffer_load_dwordx4 v6, s[12:15], s62 offen lds
	s_nop 0
	s_mov_b32 m0, s38
	s_nop 0
	buffer_load_dwordx4 v7, s[12:15], s62 offen lds
	s_waitcnt vmcnt(8)
	s_waitcnt lgkmcnt(0)
	s_setprio 1
	s_barrier
	v_mfma_i32_16x16x64_i8 v[78:81], v[10:13], v[170:173], v[78:81]
	v_mfma_i32_16x16x64_i8 v[74:77], v[146:149], v[170:173], v[74:77]
	v_mfma_i32_16x16x64_i8 v[62:65], v[10:13], v[178:181], v[62:65]
	v_mfma_i32_16x16x64_i8 v[58:61], v[146:149], v[178:181], v[58:61]
	v_mfma_i32_16x16x64_i8 v[46:49], v[10:13], v[186:189], v[46:49]
	v_mfma_i32_16x16x64_i8 v[42:45], v[146:149], v[186:189], v[42:45]
	v_mfma_i32_16x16x64_i8 v[10:13], v[10:13], v[194:197], v[30:33]
	v_mfma_i32_16x16x64_i8 v[78:81], v[14:17], v[174:177], v[78:81]
	v_mfma_i32_16x16x64_i8 v[74:77], v[150:153], v[174:177], v[74:77]
	v_mfma_i32_16x16x64_i8 v[62:65], v[14:17], v[182:185], v[62:65]
	v_mfma_i32_16x16x64_i8 v[58:61], v[150:153], v[182:185], v[58:61]
	v_mfma_i32_16x16x64_i8 v[46:49], v[14:17], v[190:193], v[46:49]
	v_mfma_i32_16x16x64_i8 v[42:45], v[150:153], v[190:193], v[42:45]
	v_mfma_i32_16x16x64_i8 v[10:13], v[14:17], v[198:201], v[10:13]
	v_mfma_i32_16x16x64_i8 v[14:17], v[146:149], v[194:197], v[26:29]
	v_mfma_i32_16x16x64_i8 v[14:17], v[150:153], v[198:201], v[14:17]
	v_mfma_i32_16x16x64_i8 v[26:29], v[154:157], v[170:173], v[70:73]
	v_mfma_i32_16x16x64_i8 v[70:73], v[158:161], v[174:177], v[26:29]
	v_mfma_i32_16x16x64_i8 v[26:29], v[162:165], v[170:173], v[66:69]
	v_mfma_i32_16x16x64_i8 v[66:69], v[166:169], v[174:177], v[26:29]
	v_mfma_i32_16x16x64_i8 v[26:29], v[154:157], v[178:181], v[54:57]
	v_mfma_i32_16x16x64_i8 v[54:57], v[158:161], v[182:185], v[26:29]
	v_mfma_i32_16x16x64_i8 v[26:29], v[162:165], v[178:181], v[50:53]
	v_mfma_i32_16x16x64_i8 v[50:53], v[166:169], v[182:185], v[26:29]
	v_mfma_i32_16x16x64_i8 v[26:29], v[154:157], v[186:189], v[38:41]
	v_mfma_i32_16x16x64_i8 v[38:41], v[158:161], v[190:193], v[26:29]
	v_mfma_i32_16x16x64_i8 v[26:29], v[162:165], v[186:189], v[34:37]
	v_mfma_i32_16x16x64_i8 v[22:25], v[154:157], v[194:197], v[22:25]
	v_mfma_i32_16x16x64_i8 v[18:21], v[162:165], v[194:197], v[18:21]
	v_mfma_i32_16x16x64_i8 v[34:37], v[166:169], v[190:193], v[26:29]
	v_mfma_i32_16x16x64_i8 v[22:25], v[158:161], v[198:201], v[22:25]
	v_mfma_i32_16x16x64_i8 v[18:21], v[166:169], v[198:201], v[18:21]
	s_barrier
	s_setprio 0
	v_add_u32_e32 v150, 0x18000, v8
	v_add_u32_e32 v166, 0x1c000, v8
	ds_read_b128 v[26:29], v150
	ds_read_b128 v[30:33], v150 offset:1024
	ds_read_b128 v[146:149], v150 offset:2048
	ds_read_b128 v[150:153], v150 offset:3072
	ds_read_b128 v[154:157], v166
	ds_read_b128 v[158:161], v166 offset:1024
	ds_read_b128 v[162:165], v166 offset:2048
	ds_read_b128 v[166:169], v166 offset:3072
	s_add_i32 s61, s62, 0x20000
	s_mov_b32 m0, s40
	s_nop 0
	buffer_load_dwordx4 v6, s[12:15], s61 offen lds
	s_nop 0
	s_mov_b32 m0, s41
	s_nop 0
	buffer_load_dwordx4 v7, s[12:15], s61 offen lds
	ds_read_b128 v[170:173], v9 offset:32768
	ds_read_b128 v[174:177], v9 offset:33792
	ds_read_b128 v[178:181], v9 offset:34816
	ds_read_b128 v[182:185], v9 offset:35840
	ds_read_b128 v[186:189], v9 offset:36864
	ds_read_b128 v[190:193], v9 offset:37888
	ds_read_b128 v[194:197], v9 offset:38912
	ds_read_b128 v[198:201], v9 offset:39936
	s_waitcnt vmcnt(8)
	s_waitcnt lgkmcnt(0)
	s_setprio 1
	s_barrier
	v_mfma_i32_16x16x64_i8 v[142:145], v[26:29], v[170:173], v[142:145]
	v_mfma_i32_16x16x64_i8 v[138:141], v[146:149], v[170:173], v[138:141]
	v_mfma_i32_16x16x64_i8 v[126:129], v[26:29], v[178:181], v[126:129]
	v_mfma_i32_16x16x64_i8 v[122:125], v[146:149], v[178:181], v[122:125]
	v_mfma_i32_16x16x64_i8 v[110:113], v[26:29], v[186:189], v[110:113]
	v_mfma_i32_16x16x64_i8 v[106:109], v[146:149], v[186:189], v[106:109]
	v_mfma_i32_16x16x64_i8 v[94:97], v[26:29], v[194:197], v[94:97]
	v_mfma_i32_16x16x64_i8 v[90:93], v[146:149], v[194:197], v[90:93]
	v_mfma_i32_16x16x64_i8 v[142:145], v[30:33], v[174:177], v[142:145]
	v_mfma_i32_16x16x64_i8 v[138:141], v[150:153], v[174:177], v[138:141]
	v_mfma_i32_16x16x64_i8 v[126:129], v[30:33], v[182:185], v[126:129]
	v_mfma_i32_16x16x64_i8 v[122:125], v[150:153], v[182:185], v[122:125]
	v_mfma_i32_16x16x64_i8 v[110:113], v[30:33], v[190:193], v[110:113]
	v_mfma_i32_16x16x64_i8 v[106:109], v[150:153], v[190:193], v[106:109]
	v_mfma_i32_16x16x64_i8 v[94:97], v[30:33], v[198:201], v[94:97]
	v_mfma_i32_16x16x64_i8 v[90:93], v[150:153], v[198:201], v[90:93]
	v_mfma_i32_16x16x64_i8 v[134:137], v[154:157], v[170:173], v[134:137]
	v_mfma_i32_16x16x64_i8 v[130:133], v[162:165], v[170:173], v[130:133]
	v_mfma_i32_16x16x64_i8 v[118:121], v[154:157], v[178:181], v[118:121]
	v_mfma_i32_16x16x64_i8 v[114:117], v[162:165], v[178:181], v[114:117]
	v_mfma_i32_16x16x64_i8 v[102:105], v[154:157], v[186:189], v[102:105]
	v_mfma_i32_16x16x64_i8 v[98:101], v[162:165], v[186:189], v[98:101]
	v_mfma_i32_16x16x64_i8 v[86:89], v[154:157], v[194:197], v[86:89]
	v_mfma_i32_16x16x64_i8 v[82:85], v[162:165], v[194:197], v[82:85]
	v_mfma_i32_16x16x64_i8 v[134:137], v[158:161], v[174:177], v[134:137]
	v_mfma_i32_16x16x64_i8 v[130:133], v[166:169], v[174:177], v[130:133]
	v_mfma_i32_16x16x64_i8 v[118:121], v[158:161], v[182:185], v[118:121]
	v_mfma_i32_16x16x64_i8 v[114:117], v[166:169], v[182:185], v[114:117]
	v_mfma_i32_16x16x64_i8 v[102:105], v[158:161], v[190:193], v[102:105]
	v_mfma_i32_16x16x64_i8 v[98:101], v[166:169], v[190:193], v[98:101]
	v_mfma_i32_16x16x64_i8 v[86:89], v[158:161], v[198:201], v[86:89]
	v_mfma_i32_16x16x64_i8 v[82:85], v[166:169], v[198:201], v[82:85]
	s_barrier
	s_setprio 0
	ds_read_b128 v[170:173], v9 offset:49152
	ds_read_b128 v[174:177], v9 offset:50176
	s_or_b32 s61, s60, 0x80
	s_mov_b32 m0, s42
	s_nop 0
	buffer_load_dwordx4 v6, s[8:11], s61 offen lds
	ds_read_b128 v[178:181], v9 offset:51200
	ds_read_b128 v[182:185], v9 offset:52224
	s_add_i32 s60, s60, 0x20080
	s_mov_b32 m0, s43
	s_nop 0
	buffer_load_dwordx4 v7, s[8:11], s61 offen lds
	ds_read_b128 v[186:189], v9 offset:53248
	ds_read_b128 v[190:193], v9 offset:54272
	s_nop 0
	s_mov_b32 m0, s46
	s_nop 0
	buffer_load_dwordx4 v6, s[8:11], s60 offen lds
	ds_read_b128 v[194:197], v9 offset:55296
	ds_read_b128 v[198:201], v9 offset:56320
	s_nop 0
	s_mov_b32 m0, s47
	s_nop 0
	buffer_load_dwordx4 v7, s[8:11], s60 offen lds
	s_nop 0
	s_mov_b32 m0, s44
	s_nop 0
	buffer_load_dwordx4 v6, s[12:15], s59 offen lds
	s_nop 0
	s_mov_b32 m0, s45
	s_nop 0
	buffer_load_dwordx4 v7, s[12:15], s59 offen lds
	s_waitcnt vmcnt(8)
	s_waitcnt lgkmcnt(0)
	s_setprio 1
	s_barrier
	v_mfma_i32_16x16x64_i8 v[78:81], v[26:29], v[170:173], v[78:81]
	v_mfma_i32_16x16x64_i8 v[62:65], v[26:29], v[178:181], v[62:65]
	v_mfma_i32_16x16x64_i8 v[46:49], v[26:29], v[186:189], v[46:49]
	v_mfma_i32_16x16x64_i8 v[10:13], v[26:29], v[194:197], v[10:13]
	v_mfma_i32_16x16x64_i8 v[78:81], v[30:33], v[174:177], v[78:81]
	v_mfma_i32_16x16x64_i8 v[74:77], v[146:149], v[170:173], v[74:77]
	v_mfma_i32_16x16x64_i8 v[62:65], v[30:33], v[182:185], v[62:65]
	v_mfma_i32_16x16x64_i8 v[58:61], v[146:149], v[178:181], v[58:61]
	v_mfma_i32_16x16x64_i8 v[46:49], v[30:33], v[190:193], v[46:49]
	v_mfma_i32_16x16x64_i8 v[42:45], v[146:149], v[186:189], v[42:45]
	v_mfma_i32_16x16x64_i8 v[30:33], v[30:33], v[198:201], v[10:13]
	v_mfma_i32_16x16x64_i8 v[10:13], v[146:149], v[194:197], v[14:17]
	v_mfma_i32_16x16x64_i8 v[74:77], v[150:153], v[174:177], v[74:77]
	v_mfma_i32_16x16x64_i8 v[58:61], v[150:153], v[182:185], v[58:61]
	v_mfma_i32_16x16x64_i8 v[42:45], v[150:153], v[190:193], v[42:45]
	v_mfma_i32_16x16x64_i8 v[26:29], v[150:153], v[198:201], v[10:13]
	v_mfma_i32_16x16x64_i8 v[10:13], v[154:157], v[170:173], v[70:73]
	v_mfma_i32_16x16x64_i8 v[70:73], v[158:161], v[174:177], v[10:13]
	v_mfma_i32_16x16x64_i8 v[10:13], v[162:165], v[170:173], v[66:69]
	v_mfma_i32_16x16x64_i8 v[66:69], v[166:169], v[174:177], v[10:13]
	v_mfma_i32_16x16x64_i8 v[10:13], v[154:157], v[178:181], v[54:57]
	v_mfma_i32_16x16x64_i8 v[54:57], v[158:161], v[182:185], v[10:13]
	v_mfma_i32_16x16x64_i8 v[10:13], v[162:165], v[178:181], v[50:53]
	v_mfma_i32_16x16x64_i8 v[50:53], v[166:169], v[182:185], v[10:13]
	v_mfma_i32_16x16x64_i8 v[10:13], v[154:157], v[186:189], v[38:41]
	v_mfma_i32_16x16x64_i8 v[38:41], v[158:161], v[190:193], v[10:13]
	v_mfma_i32_16x16x64_i8 v[10:13], v[162:165], v[186:189], v[34:37]
	v_mfma_i32_16x16x64_i8 v[34:37], v[166:169], v[190:193], v[10:13]
	v_mfma_i32_16x16x64_i8 v[10:13], v[154:157], v[194:197], v[22:25]
	v_mfma_i32_16x16x64_i8 v[22:25], v[158:161], v[198:201], v[10:13]
	v_mfma_i32_16x16x64_i8 v[10:13], v[162:165], v[194:197], v[18:21]
	v_mfma_i32_16x16x64_i8 v[18:21], v[166:169], v[198:201], v[10:13]
	s_barrier
	s_setprio 0
	s_add_i32 s55, s55, 2
	s_addk_i32 s58, 0x100
	s_cmp_lt_u32 s55, 6
	s_cbranch_scc1 .LBB0_943
	s_andn2_b64 vcc, exec, s[6:7]
	s_cbranch_vccz .LBB0_935
	v_cvt_f32_i32_e32 v142, v142
	v_cvt_f32_i32_e32 v143, v143
	v_cvt_f32_i32_e32 v144, v144
	v_cvt_f32_i32_e32 v145, v145
	v_cvt_f32_i32_e32 v138, v138
	v_cvt_f32_i32_e32 v139, v139
	v_cvt_f32_i32_e32 v140, v140
	v_cvt_f32_i32_e32 v141, v141
	v_cvt_f32_i32_e32 v126, v126
	v_cvt_f32_i32_e32 v127, v127
	v_cvt_f32_i32_e32 v128, v128
	v_cvt_f32_i32_e32 v129, v129
	v_cvt_f32_i32_e32 v122, v122
	v_cvt_f32_i32_e32 v123, v123
	v_cvt_f32_i32_e32 v124, v124
	v_cvt_f32_i32_e32 v125, v125
	v_cvt_f32_i32_e32 v110, v110
	v_cvt_f32_i32_e32 v111, v111
	v_cvt_f32_i32_e32 v112, v112
	v_cvt_f32_i32_e32 v113, v113
	v_cvt_f32_i32_e32 v106, v106
	v_cvt_f32_i32_e32 v107, v107
	v_cvt_f32_i32_e32 v108, v108
	v_cvt_f32_i32_e32 v109, v109
	v_cvt_f32_i32_e32 v94, v94
	v_cvt_f32_i32_e32 v95, v95
	v_cvt_f32_i32_e32 v96, v96
	v_cvt_f32_i32_e32 v97, v97
	v_cvt_f32_i32_e32 v90, v90
	v_cvt_f32_i32_e32 v91, v91
	v_cvt_f32_i32_e32 v92, v92
	v_cvt_f32_i32_e32 v93, v93
	v_cvt_f32_i32_e32 v134, v134
	v_cvt_f32_i32_e32 v135, v135
	v_cvt_f32_i32_e32 v136, v136
	v_cvt_f32_i32_e32 v137, v137
	v_cvt_f32_i32_e32 v130, v130
	v_cvt_f32_i32_e32 v131, v131
	v_cvt_f32_i32_e32 v132, v132
	v_cvt_f32_i32_e32 v133, v133
	v_cvt_f32_i32_e32 v118, v118
	v_cvt_f32_i32_e32 v119, v119
	v_cvt_f32_i32_e32 v120, v120
	v_cvt_f32_i32_e32 v121, v121
	v_cvt_f32_i32_e32 v114, v114
	v_cvt_f32_i32_e32 v115, v115
	v_cvt_f32_i32_e32 v116, v116
	v_cvt_f32_i32_e32 v117, v117
	v_cvt_f32_i32_e32 v102, v102
	v_cvt_f32_i32_e32 v103, v103
	v_cvt_f32_i32_e32 v104, v104
	v_cvt_f32_i32_e32 v105, v105
	v_cvt_f32_i32_e32 v98, v98
	v_cvt_f32_i32_e32 v99, v99
	v_cvt_f32_i32_e32 v100, v100
	v_cvt_f32_i32_e32 v101, v101
	v_cvt_f32_i32_e32 v86, v86
	v_cvt_f32_i32_e32 v87, v87
	v_cvt_f32_i32_e32 v88, v88
	v_cvt_f32_i32_e32 v89, v89
	v_cvt_f32_i32_e32 v82, v82
	v_cvt_f32_i32_e32 v83, v83
	v_cvt_f32_i32_e32 v84, v84
	v_cvt_f32_i32_e32 v85, v85
	v_cvt_f32_i32_e32 v78, v78
	v_cvt_f32_i32_e32 v79, v79
	v_cvt_f32_i32_e32 v80, v80
	v_cvt_f32_i32_e32 v81, v81
	v_cvt_f32_i32_e32 v74, v74
	v_cvt_f32_i32_e32 v75, v75
	v_cvt_f32_i32_e32 v76, v76
	v_cvt_f32_i32_e32 v77, v77
	v_cvt_f32_i32_e32 v62, v62
	v_cvt_f32_i32_e32 v63, v63
	v_cvt_f32_i32_e32 v64, v64
	v_cvt_f32_i32_e32 v65, v65
	v_cvt_f32_i32_e32 v58, v58
	v_cvt_f32_i32_e32 v59, v59
	v_cvt_f32_i32_e32 v60, v60
	v_cvt_f32_i32_e32 v61, v61
	v_cvt_f32_i32_e32 v46, v46
	v_cvt_f32_i32_e32 v47, v47
	v_cvt_f32_i32_e32 v48, v48
	v_cvt_f32_i32_e32 v49, v49
	v_cvt_f32_i32_e32 v42, v42
	v_cvt_f32_i32_e32 v43, v43
	v_cvt_f32_i32_e32 v44, v44
	v_cvt_f32_i32_e32 v45, v45
	v_cvt_f32_i32_e32 v30, v30
	v_cvt_f32_i32_e32 v31, v31
	v_cvt_f32_i32_e32 v32, v32
	v_cvt_f32_i32_e32 v33, v33
	v_cvt_f32_i32_e32 v26, v26
	v_cvt_f32_i32_e32 v27, v27
	v_cvt_f32_i32_e32 v28, v28
	v_cvt_f32_i32_e32 v29, v29
	v_cvt_f32_i32_e32 v70, v70
	v_cvt_f32_i32_e32 v71, v71
	v_cvt_f32_i32_e32 v72, v72
	v_cvt_f32_i32_e32 v73, v73
	v_cvt_f32_i32_e32 v66, v66
	v_cvt_f32_i32_e32 v67, v67
	v_cvt_f32_i32_e32 v68, v68
	v_cvt_f32_i32_e32 v69, v69
	v_cvt_f32_i32_e32 v54, v54
	v_cvt_f32_i32_e32 v55, v55
	v_cvt_f32_i32_e32 v56, v56
	v_cvt_f32_i32_e32 v57, v57
	v_cvt_f32_i32_e32 v50, v50
	v_cvt_f32_i32_e32 v51, v51
	v_cvt_f32_i32_e32 v52, v52
	v_cvt_f32_i32_e32 v53, v53
	v_cvt_f32_i32_e32 v38, v38
	v_cvt_f32_i32_e32 v39, v39
	v_cvt_f32_i32_e32 v40, v40
	v_cvt_f32_i32_e32 v41, v41
	v_cvt_f32_i32_e32 v34, v34
	v_cvt_f32_i32_e32 v35, v35
	v_cvt_f32_i32_e32 v36, v36
	v_cvt_f32_i32_e32 v37, v37
	v_cvt_f32_i32_e32 v22, v22
	v_cvt_f32_i32_e32 v23, v23
	v_cvt_f32_i32_e32 v24, v24
	v_cvt_f32_i32_e32 v25, v25
	v_cvt_f32_i32_e32 v18, v18
	v_cvt_f32_i32_e32 v19, v19
	v_cvt_f32_i32_e32 v20, v20
	v_cvt_f32_i32_e32 v21, v21
	s_andn2_b64 vcc, exec, s[4:5]
	s_cbranch_vccnz .LBB0_936

.LBB0_1072:
	ds_read_b128 v[136:139], v152
	ds_read_b128 v[140:143], v152 offset:1024
	ds_read_b128 v[158:161], v152 offset:2048
	ds_read_b128 v[162:165], v152 offset:3072
	ds_read_b128 v[166:169], v153
	ds_read_b128 v[170:173], v153 offset:1024
	ds_read_b128 v[174:177], v153 offset:2048
	ds_read_b128 v[178:181], v153 offset:3072
	s_add_i32 s60, s55, 0xfffe0080
	s_cmp_eq_u32 s59, 4
	s_cselect_b32 s62, s1, s60
	s_cselect_b32 s61, s54, s58
	s_or_b32 s60, s62, 0x80
	s_mov_b32 m0, s42
	s_nop 0
	buffer_load_dwordx4 v146, s[12:15], s55 offen lds
	s_nop 0
	s_mov_b32 m0, s43
	s_nop 0
	buffer_load_dwordx4 v147, s[12:15], s55 offen lds
	ds_read_b128 v[182:185], v154
	ds_read_b128 v[186:189], v154 offset:1024
	ds_read_b128 v[190:193], v154 offset:2048
	ds_read_b128 v[194:197], v154 offset:3072
	ds_read_b128 v[198:201], v154 offset:4096
	ds_read_b128 v[202:205], v154 offset:5120
	ds_read_b128 v[206:209], v154 offset:6144
	ds_read_b128 v[210:213], v154 offset:7168
	s_waitcnt vmcnt(8)
	s_waitcnt lgkmcnt(0)
	s_setprio 1
	s_barrier
	v_mfma_i32_16x16x64_i8 v[126:129], v[136:139], v[182:185], v[126:129]
	v_mfma_i32_16x16x64_i8 v[122:125], v[158:161], v[182:185], v[122:125]
	v_mfma_i32_16x16x64_i8 v[118:121], v[136:139], v[190:193], v[118:121]
	v_mfma_i32_16x16x64_i8 v[114:117], v[158:161], v[190:193], v[114:117]
	v_mfma_i32_16x16x64_i8 v[110:113], v[136:139], v[198:201], v[110:113]
	v_mfma_i32_16x16x64_i8 v[106:109], v[158:161], v[198:201], v[106:109]
	v_mfma_i32_16x16x64_i8 v[102:105], v[136:139], v[206:209], v[102:105]
	v_mfma_i32_16x16x64_i8 v[98:101], v[158:161], v[206:209], v[98:101]
	v_mfma_i32_16x16x64_i8 v[126:129], v[140:143], v[186:189], v[126:129]
	v_mfma_i32_16x16x64_i8 v[122:125], v[162:165], v[186:189], v[122:125]
	v_mfma_i32_16x16x64_i8 v[118:121], v[140:143], v[194:197], v[118:121]
	v_mfma_i32_16x16x64_i8 v[114:117], v[162:165], v[194:197], v[114:117]
	v_mfma_i32_16x16x64_i8 v[110:113], v[140:143], v[202:205], v[110:113]
	v_mfma_i32_16x16x64_i8 v[106:109], v[162:165], v[202:205], v[106:109]
	v_mfma_i32_16x16x64_i8 v[102:105], v[140:143], v[210:213], v[102:105]
	v_mfma_i32_16x16x64_i8 v[98:101], v[162:165], v[210:213], v[98:101]
	v_mfma_i32_16x16x64_i8 v[94:97], v[166:169], v[182:185], v[94:97]
	v_mfma_i32_16x16x64_i8 v[90:93], v[174:177], v[182:185], v[90:93]
	v_mfma_i32_16x16x64_i8 v[86:89], v[166:169], v[190:193], v[86:89]
	v_mfma_i32_16x16x64_i8 v[82:85], v[174:177], v[190:193], v[82:85]
	v_mfma_i32_16x16x64_i8 v[78:81], v[166:169], v[198:201], v[78:81]
	v_mfma_i32_16x16x64_i8 v[74:77], v[174:177], v[198:201], v[74:77]
	v_mfma_i32_16x16x64_i8 v[70:73], v[166:169], v[206:209], v[70:73]
	v_mfma_i32_16x16x64_i8 v[66:69], v[174:177], v[206:209], v[66:69]
	v_mfma_i32_16x16x64_i8 v[94:97], v[170:173], v[186:189], v[94:97]
	v_mfma_i32_16x16x64_i8 v[90:93], v[178:181], v[186:189], v[90:93]
	v_mfma_i32_16x16x64_i8 v[86:89], v[170:173], v[194:197], v[86:89]
	v_mfma_i32_16x16x64_i8 v[82:85], v[178:181], v[194:197], v[82:85]
	v_mfma_i32_16x16x64_i8 v[78:81], v[170:173], v[202:205], v[78:81]
	v_mfma_i32_16x16x64_i8 v[74:77], v[178:181], v[202:205], v[74:77]
	v_mfma_i32_16x16x64_i8 v[70:73], v[170:173], v[210:213], v[70:73]
	v_mfma_i32_16x16x64_i8 v[66:69], v[178:181], v[210:213], v[66:69]
	s_barrier
	s_setprio 0
	ds_read_b128 v[182:185], v154 offset:16384
	ds_read_b128 v[186:189], v154 offset:17408
	s_mov_b32 m0, s27
	s_nop 0
	buffer_load_dwordx4 v144, s[8:11], s61 offen lds
	ds_read_b128 v[190:193], v154 offset:18432
	ds_read_b128 v[194:197], v154 offset:19456
	s_add_i32 s63, s61, 0x20000
	s_mov_b32 m0, s28
	s_nop 0
	buffer_load_dwordx4 v145, s[8:11], s61 offen lds
	ds_read_b128 v[198:201], v154 offset:20480
	ds_read_b128 v[202:205], v154 offset:21504
	s_nop 0
	s_mov_b32 m0, s29
	s_nop 0
	buffer_load_dwordx4 v144, s[8:11], s63 offen lds
	ds_read_b128 v[206:209], v154 offset:22528
	ds_read_b128 v[210:213], v154 offset:23552
	s_nop 0
	s_mov_b32 m0, s30
	s_nop 0
	buffer_load_dwordx4 v145, s[8:11], s63 offen lds
	s_nop 0
	s_mov_b32 m0, s26
	s_nop 0
	buffer_load_dwordx4 v146, s[12:15], s62 offen lds
	s_nop 0
	s_mov_b32 m0, s2
	s_nop 0
	buffer_load_dwordx4 v147, s[12:15], s62 offen lds
	s_waitcnt vmcnt(8)
	s_waitcnt lgkmcnt(0)
	s_setprio 1
	s_barrier
	v_mfma_i32_16x16x64_i8 v[62:65], v[136:139], v[182:185], v[62:65]
	v_mfma_i32_16x16x64_i8 v[58:61], v[158:161], v[182:185], v[58:61]
	v_mfma_i32_16x16x64_i8 v[54:57], v[136:139], v[190:193], v[54:57]
	v_mfma_i32_16x16x64_i8 v[50:53], v[158:161], v[190:193], v[50:53]
	v_mfma_i32_16x16x64_i8 v[46:49], v[136:139], v[198:201], v[46:49]
	v_mfma_i32_16x16x64_i8 v[42:45], v[158:161], v[198:201], v[42:45]
	v_mfma_i32_16x16x64_i8 v[38:41], v[136:139], v[206:209], v[38:41]
	v_mfma_i32_16x16x64_i8 v[34:37], v[158:161], v[206:209], v[34:37]
	v_mfma_i32_16x16x64_i8 v[62:65], v[140:143], v[186:189], v[62:65]
	v_mfma_i32_16x16x64_i8 v[58:61], v[162:165], v[186:189], v[58:61]
	v_mfma_i32_16x16x64_i8 v[54:57], v[140:143], v[194:197], v[54:57]
	v_mfma_i32_16x16x64_i8 v[50:53], v[162:165], v[194:197], v[50:53]
	v_mfma_i32_16x16x64_i8 v[46:49], v[140:143], v[202:205], v[46:49]
	v_mfma_i32_16x16x64_i8 v[42:45], v[162:165], v[202:205], v[42:45]
	v_mfma_i32_16x16x64_i8 v[38:41], v[140:143], v[210:213], v[38:41]
	v_mfma_i32_16x16x64_i8 v[34:37], v[162:165], v[210:213], v[34:37]
	v_mfma_i32_16x16x64_i8 v[30:33], v[166:169], v[182:185], v[30:33]
	v_mfma_i32_16x16x64_i8 v[26:29], v[174:177], v[182:185], v[26:29]
	v_mfma_i32_16x16x64_i8 v[22:25], v[166:169], v[190:193], v[22:25]
	v_mfma_i32_16x16x64_i8 v[18:21], v[174:177], v[190:193], v[18:21]
	v_mfma_i32_16x16x64_i8 v[14:17], v[166:169], v[198:201], v[14:17]
	v_mfma_i32_16x16x64_i8 v[10:13], v[174:177], v[198:201], v[10:13]
	v_mfma_i32_16x16x64_i8 v[6:9], v[166:169], v[206:209], v[6:9]
	v_mfma_i32_16x16x64_i8 v[2:5], v[174:177], v[206:209], v[2:5]
	v_mfma_i32_16x16x64_i8 v[30:33], v[170:173], v[186:189], v[30:33]
	v_mfma_i32_16x16x64_i8 v[26:29], v[178:181], v[186:189], v[26:29]
	v_mfma_i32_16x16x64_i8 v[22:25], v[170:173], v[194:197], v[22:25]
	v_mfma_i32_16x16x64_i8 v[18:21], v[178:181], v[194:197], v[18:21]
	v_mfma_i32_16x16x64_i8 v[14:17], v[170:173], v[202:205], v[14:17]
	v_mfma_i32_16x16x64_i8 v[10:13], v[178:181], v[202:205], v[10:13]
	v_mfma_i32_16x16x64_i8 v[6:9], v[170:173], v[210:213], v[6:9]
	v_mfma_i32_16x16x64_i8 v[2:5], v[178:181], v[210:213], v[2:5]
	s_barrier
	s_setprio 0
	ds_read_b128 v[136:139], v155
	ds_read_b128 v[140:143], v155 offset:1024
	ds_read_b128 v[158:161], v155 offset:2048
	ds_read_b128 v[162:165], v155 offset:3072
	ds_read_b128 v[166:169], v156
	ds_read_b128 v[170:173], v156 offset:1024
	ds_read_b128 v[174:177], v156 offset:2048
	ds_read_b128 v[178:181], v156 offset:3072
	s_add_i32 s62, s62, 0x20000
	s_mov_b32 m0, s3
	s_nop 0
	buffer_load_dwordx4 v146, s[12:15], s62 offen lds
	s_nop 0
	s_mov_b32 m0, s31
	s_nop 0
	buffer_load_dwordx4 v147, s[12:15], s62 offen lds
	ds_read_b128 v[182:185], v154 offset:32768
	ds_read_b128 v[186:189], v154 offset:33792
	ds_read_b128 v[190:193], v154 offset:34816
	ds_read_b128 v[194:197], v154 offset:35840
	ds_read_b128 v[198:201], v154 offset:36864
	ds_read_b128 v[202:205], v154 offset:37888
	ds_read_b128 v[206:209], v154 offset:38912
	ds_read_b128 v[210:213], v154 offset:39936
	s_waitcnt vmcnt(8)
	s_waitcnt lgkmcnt(0)
	s_setprio 1
	s_barrier
	v_mfma_i32_16x16x64_i8 v[126:129], v[136:139], v[182:185], v[126:129]
	v_mfma_i32_16x16x64_i8 v[122:125], v[158:161], v[182:185], v[122:125]
	v_mfma_i32_16x16x64_i8 v[118:121], v[136:139], v[190:193], v[118:121]
	v_mfma_i32_16x16x64_i8 v[114:117], v[158:161], v[190:193], v[114:117]
	v_mfma_i32_16x16x64_i8 v[110:113], v[136:139], v[198:201], v[110:113]
	v_mfma_i32_16x16x64_i8 v[106:109], v[158:161], v[198:201], v[106:109]
	v_mfma_i32_16x16x64_i8 v[102:105], v[136:139], v[206:209], v[102:105]
	v_mfma_i32_16x16x64_i8 v[98:101], v[158:161], v[206:209], v[98:101]
	v_mfma_i32_16x16x64_i8 v[126:129], v[140:143], v[186:189], v[126:129]
	v_mfma_i32_16x16x64_i8 v[122:125], v[162:165], v[186:189], v[122:125]
	v_mfma_i32_16x16x64_i8 v[118:121], v[140:143], v[194:197], v[118:121]
	v_mfma_i32_16x16x64_i8 v[114:117], v[162:165], v[194:197], v[114:117]
	v_mfma_i32_16x16x64_i8 v[110:113], v[140:143], v[202:205], v[110:113]
	v_mfma_i32_16x16x64_i8 v[106:109], v[162:165], v[202:205], v[106:109]
	v_mfma_i32_16x16x64_i8 v[102:105], v[140:143], v[210:213], v[102:105]
	v_mfma_i32_16x16x64_i8 v[98:101], v[162:165], v[210:213], v[98:101]
	v_mfma_i32_16x16x64_i8 v[94:97], v[166:169], v[182:185], v[94:97]
	v_mfma_i32_16x16x64_i8 v[90:93], v[174:177], v[182:185], v[90:93]
	v_mfma_i32_16x16x64_i8 v[86:89], v[166:169], v[190:193], v[86:89]
	v_mfma_i32_16x16x64_i8 v[82:85], v[174:177], v[190:193], v[82:85]
	v_mfma_i32_16x16x64_i8 v[78:81], v[166:169], v[198:201], v[78:81]
	v_mfma_i32_16x16x64_i8 v[74:77], v[174:177], v[198:201], v[74:77]
	v_mfma_i32_16x16x64_i8 v[70:73], v[166:169], v[206:209], v[70:73]
	v_mfma_i32_16x16x64_i8 v[66:69], v[174:177], v[206:209], v[66:69]
	v_mfma_i32_16x16x64_i8 v[94:97], v[170:173], v[186:189], v[94:97]
	v_mfma_i32_16x16x64_i8 v[90:93], v[178:181], v[186:189], v[90:93]
	v_mfma_i32_16x16x64_i8 v[86:89], v[170:173], v[194:197], v[86:89]
	v_mfma_i32_16x16x64_i8 v[82:85], v[178:181], v[194:197], v[82:85]
	v_mfma_i32_16x16x64_i8 v[78:81], v[170:173], v[202:205], v[78:81]
	v_mfma_i32_16x16x64_i8 v[74:77], v[178:181], v[202:205], v[74:77]
	v_mfma_i32_16x16x64_i8 v[70:73], v[170:173], v[210:213], v[70:73]
	v_mfma_i32_16x16x64_i8 v[66:69], v[178:181], v[210:213], v[66:69]
	s_barrier
	s_setprio 0
	ds_read_b128 v[182:185], v154 offset:49152
	ds_read_b128 v[186:189], v154 offset:50176
	s_or_b32 s62, s61, 0x80
	s_mov_b32 m0, s35
	s_nop 0
	buffer_load_dwordx4 v144, s[8:11], s62 offen lds
	ds_read_b128 v[190:193], v154 offset:51200
	ds_read_b128 v[194:197], v154 offset:52224
	s_add_i32 s61, s61, 0x20080
	s_mov_b32 m0, s36
	s_nop 0
	buffer_load_dwordx4 v145, s[8:11], s62 offen lds
	ds_read_b128 v[198:201], v154 offset:53248
	ds_read_b128 v[202:205], v154 offset:54272
	s_nop 0
	s_mov_b32 m0, s39
	s_nop 0
	buffer_load_dwordx4 v144, s[8:11], s61 offen lds
	ds_read_b128 v[206:209], v154 offset:55296
	ds_read_b128 v[210:213], v154 offset:56320
	s_nop 0
	s_mov_b32 m0, s40
	s_nop 0
	buffer_load_dwordx4 v145, s[8:11], s61 offen lds
	s_nop 0
	s_mov_b32 m0, s37
	s_nop 0
	buffer_load_dwordx4 v146, s[12:15], s60 offen lds
	s_nop 0
	s_mov_b32 m0, s38
	s_nop 0
	buffer_load_dwordx4 v147, s[12:15], s60 offen lds
	s_waitcnt vmcnt(8)
	s_waitcnt lgkmcnt(0)
	s_setprio 1
	s_barrier
	v_mfma_i32_16x16x64_i8 v[62:65], v[136:139], v[182:185], v[62:65]
	v_mfma_i32_16x16x64_i8 v[58:61], v[158:161], v[182:185], v[58:61]
	v_mfma_i32_16x16x64_i8 v[54:57], v[136:139], v[190:193], v[54:57]
	v_mfma_i32_16x16x64_i8 v[50:53], v[158:161], v[190:193], v[50:53]
	v_mfma_i32_16x16x64_i8 v[46:49], v[136:139], v[198:201], v[46:49]
	v_mfma_i32_16x16x64_i8 v[42:45], v[158:161], v[198:201], v[42:45]
	v_mfma_i32_16x16x64_i8 v[38:41], v[136:139], v[206:209], v[38:41]
	v_mfma_i32_16x16x64_i8 v[34:37], v[158:161], v[206:209], v[34:37]
	v_mfma_i32_16x16x64_i8 v[62:65], v[140:143], v[186:189], v[62:65]
	v_mfma_i32_16x16x64_i8 v[58:61], v[162:165], v[186:189], v[58:61]
	v_mfma_i32_16x16x64_i8 v[54:57], v[140:143], v[194:197], v[54:57]
	v_mfma_i32_16x16x64_i8 v[50:53], v[162:165], v[194:197], v[50:53]
	v_mfma_i32_16x16x64_i8 v[46:49], v[140:143], v[202:205], v[46:49]
	v_mfma_i32_16x16x64_i8 v[42:45], v[162:165], v[202:205], v[42:45]
	v_mfma_i32_16x16x64_i8 v[38:41], v[140:143], v[210:213], v[38:41]
	v_mfma_i32_16x16x64_i8 v[34:37], v[162:165], v[210:213], v[34:37]
	v_mfma_i32_16x16x64_i8 v[30:33], v[166:169], v[182:185], v[30:33]
	v_mfma_i32_16x16x64_i8 v[26:29], v[174:177], v[182:185], v[26:29]
	v_mfma_i32_16x16x64_i8 v[22:25], v[166:169], v[190:193], v[22:25]
	v_mfma_i32_16x16x64_i8 v[18:21], v[174:177], v[190:193], v[18:21]
	v_mfma_i32_16x16x64_i8 v[14:17], v[166:169], v[198:201], v[14:17]
	v_mfma_i32_16x16x64_i8 v[10:13], v[174:177], v[198:201], v[10:13]
	v_mfma_i32_16x16x64_i8 v[6:9], v[166:169], v[206:209], v[6:9]
	v_mfma_i32_16x16x64_i8 v[2:5], v[174:177], v[206:209], v[2:5]
	v_mfma_i32_16x16x64_i8 v[30:33], v[170:173], v[186:189], v[30:33]
	v_mfma_i32_16x16x64_i8 v[26:29], v[178:181], v[186:189], v[26:29]
	v_mfma_i32_16x16x64_i8 v[22:25], v[170:173], v[194:197], v[22:25]
	v_mfma_i32_16x16x64_i8 v[18:21], v[178:181], v[194:197], v[18:21]
	v_mfma_i32_16x16x64_i8 v[14:17], v[170:173], v[202:205], v[14:17]
	v_mfma_i32_16x16x64_i8 v[10:13], v[178:181], v[202:205], v[10:13]
	v_mfma_i32_16x16x64_i8 v[6:9], v[170:173], v[210:213], v[6:9]
	v_mfma_i32_16x16x64_i8 v[2:5], v[178:181], v[210:213], v[2:5]
	s_barrier
	s_setprio 0
	s_add_i32 s59, s59, 2
	s_addk_i32 s55, 0x100
	s_addk_i32 s58, 0x100
	s_cmp_gt_u32 s59, 5
	s_cbranch_scc0 .LBB0_1072
	s_and_b64 vcc, exec, s[20:21]
	s_cbranch_vccz .LBB0_1075
	s_barrier

.LBB0_1135:
	v_add_u32_e32 v150, 0x10000, v136
	v_add_u32_e32 v166, 0x14000, v136
	ds_read_b128 v[138:141], v150
	ds_read_b128 v[142:145], v150 offset:1024
	ds_read_b128 v[146:149], v150 offset:2048
	ds_read_b128 v[150:153], v150 offset:3072
	ds_read_b128 v[154:157], v166
	ds_read_b128 v[158:161], v166 offset:1024
	ds_read_b128 v[162:165], v166 offset:2048
	ds_read_b128 v[166:169], v166 offset:3072
	s_add_i32 s57, s36, s3
	s_add_i32 s56, s30, s3
	s_add_i32 s55, s57, 0x1600
	s_addk_i32 s56, 0x1600
	s_cmp_eq_u32 s3, 0
	s_cselect_b32 s58, s53, s55
	s_cselect_b32 s56, s54, s56
	s_add_i32 s55, s58, 0x80
	s_add_i32 s57, s57, 0xb1580
	s_mov_b32 m0, s46
	s_nop 0
	buffer_load_dwordx4 v134, s[16:19], s57 offen lds
	s_nop 0
	s_mov_b32 m0, s47
	s_nop 0
	buffer_load_dwordx4 v135, s[16:19], s57 offen lds
	ds_read_b128 v[170:173], v137
	ds_read_b128 v[174:177], v137 offset:1024
	ds_read_b128 v[178:181], v137 offset:2048
	ds_read_b128 v[182:185], v137 offset:3072
	ds_read_b128 v[186:189], v137 offset:4096
	ds_read_b128 v[190:193], v137 offset:5120
	ds_read_b128 v[194:197], v137 offset:6144
	ds_read_b128 v[198:201], v137 offset:7168
	s_waitcnt vmcnt(8)
	s_waitcnt lgkmcnt(0)
	s_setprio 1
	s_barrier
	v_mfma_f32_16x16x32_bf16 v[126:129], v[138:141], v[170:173], v[126:129]
	v_mfma_f32_16x16x32_bf16 v[122:125], v[146:149], v[170:173], v[122:125]
	v_mfma_f32_16x16x32_bf16 v[118:121], v[138:141], v[178:181], v[118:121]
	v_mfma_f32_16x16x32_bf16 v[106:109], v[146:149], v[178:181], v[106:109]
	v_mfma_f32_16x16x32_bf16 v[102:105], v[138:141], v[186:189], v[102:105]
	v_mfma_f32_16x16x32_bf16 v[90:93], v[146:149], v[186:189], v[90:93]
	v_mfma_f32_16x16x32_bf16 v[86:89], v[138:141], v[194:197], v[86:89]
	v_mfma_f32_16x16x32_bf16 v[74:77], v[146:149], v[194:197], v[74:77]
	v_mfma_f32_16x16x32_bf16 v[126:129], v[142:145], v[174:177], v[126:129]
	v_mfma_f32_16x16x32_bf16 v[122:125], v[150:153], v[174:177], v[122:125]
	v_mfma_f32_16x16x32_bf16 v[118:121], v[142:145], v[182:185], v[118:121]
	v_mfma_f32_16x16x32_bf16 v[106:109], v[150:153], v[182:185], v[106:109]
	v_mfma_f32_16x16x32_bf16 v[102:105], v[142:145], v[190:193], v[102:105]
	v_mfma_f32_16x16x32_bf16 v[90:93], v[150:153], v[190:193], v[90:93]
	v_mfma_f32_16x16x32_bf16 v[86:89], v[142:145], v[198:201], v[86:89]
	v_mfma_f32_16x16x32_bf16 v[74:77], v[150:153], v[198:201], v[74:77]
	v_mfma_f32_16x16x32_bf16 v[114:117], v[154:157], v[170:173], v[114:117]
	v_mfma_f32_16x16x32_bf16 v[110:113], v[162:165], v[170:173], v[110:113]
	v_mfma_f32_16x16x32_bf16 v[98:101], v[154:157], v[178:181], v[98:101]
	v_mfma_f32_16x16x32_bf16 v[94:97], v[162:165], v[178:181], v[94:97]
	v_mfma_f32_16x16x32_bf16 v[82:85], v[154:157], v[186:189], v[82:85]
	v_mfma_f32_16x16x32_bf16 v[78:81], v[162:165], v[186:189], v[78:81]
	v_mfma_f32_16x16x32_bf16 v[70:73], v[154:157], v[194:197], v[70:73]
	v_mfma_f32_16x16x32_bf16 v[66:69], v[162:165], v[194:197], v[66:69]
	v_mfma_f32_16x16x32_bf16 v[114:117], v[158:161], v[174:177], v[114:117]
	v_mfma_f32_16x16x32_bf16 v[110:113], v[166:169], v[174:177], v[110:113]
	v_mfma_f32_16x16x32_bf16 v[98:101], v[158:161], v[182:185], v[98:101]
	v_mfma_f32_16x16x32_bf16 v[94:97], v[166:169], v[182:185], v[94:97]
	v_mfma_f32_16x16x32_bf16 v[82:85], v[158:161], v[190:193], v[82:85]
	v_mfma_f32_16x16x32_bf16 v[78:81], v[166:169], v[190:193], v[78:81]
	v_mfma_f32_16x16x32_bf16 v[70:73], v[158:161], v[198:201], v[70:73]
	v_mfma_f32_16x16x32_bf16 v[66:69], v[166:169], v[198:201], v[66:69]
	s_barrier
	s_setprio 0
	ds_read_b128 v[170:173], v137 offset:16384
	ds_read_b128 v[174:177], v137 offset:17408
	s_mov_b32 m0, s29
	s_nop 0
	buffer_load_dwordx4 v134, s[12:15], s56 offen lds
	ds_read_b128 v[178:181], v137 offset:18432
	ds_read_b128 v[182:185], v137 offset:19456
	s_add_i32 s57, s56, 0xb0000
	s_mov_b32 m0, s33
	s_nop 0
	buffer_load_dwordx4 v135, s[12:15], s56 offen lds
	ds_read_b128 v[186:189], v137 offset:20480
	ds_read_b128 v[190:193], v137 offset:21504
	s_nop 0
	s_mov_b32 m0, s34
	s_nop 0
	buffer_load_dwordx4 v134, s[12:15], s57 offen lds
	ds_read_b128 v[194:197], v137 offset:22528
	ds_read_b128 v[198:201], v137 offset:23552
	s_nop 0
	s_mov_b32 m0, s35
	s_nop 0
	buffer_load_dwordx4 v135, s[12:15], s57 offen lds
	s_nop 0
	s_mov_b32 m0, s28
	s_nop 0
	buffer_load_dwordx4 v134, s[16:19], s58 offen lds
	s_nop 0
	s_mov_b32 m0, s37
	s_nop 0
	buffer_load_dwordx4 v135, s[16:19], s58 offen lds
	s_waitcnt vmcnt(8)
	s_waitcnt lgkmcnt(0)
	s_setprio 1
	s_barrier
	v_mfma_f32_16x16x32_bf16 v[62:65], v[138:141], v[170:173], v[62:65]
	v_mfma_f32_16x16x32_bf16 v[58:61], v[146:149], v[170:173], v[58:61]
	v_mfma_f32_16x16x32_bf16 v[54:57], v[138:141], v[178:181], v[54:57]
	v_mfma_f32_16x16x32_bf16 v[42:45], v[146:149], v[178:181], v[42:45]
	v_mfma_f32_16x16x32_bf16 v[38:41], v[138:141], v[186:189], v[38:41]
	v_mfma_f32_16x16x32_bf16 v[26:29], v[146:149], v[186:189], v[26:29]
	v_mfma_f32_16x16x32_bf16 v[18:21], v[138:141], v[194:197], v[18:21]
	v_mfma_f32_16x16x32_bf16 v[10:13], v[146:149], v[194:197], v[10:13]
	v_mfma_f32_16x16x32_bf16 v[62:65], v[142:145], v[174:177], v[62:65]
	v_mfma_f32_16x16x32_bf16 v[58:61], v[150:153], v[174:177], v[58:61]
	v_mfma_f32_16x16x32_bf16 v[54:57], v[142:145], v[182:185], v[54:57]
	v_mfma_f32_16x16x32_bf16 v[42:45], v[150:153], v[182:185], v[42:45]
	v_mfma_f32_16x16x32_bf16 v[38:41], v[142:145], v[190:193], v[38:41]
	v_mfma_f32_16x16x32_bf16 v[26:29], v[150:153], v[190:193], v[26:29]
	v_mfma_f32_16x16x32_bf16 v[18:21], v[142:145], v[198:201], v[18:21]
	v_mfma_f32_16x16x32_bf16 v[10:13], v[150:153], v[198:201], v[10:13]
	v_mfma_f32_16x16x32_bf16 v[50:53], v[154:157], v[170:173], v[50:53]
	v_mfma_f32_16x16x32_bf16 v[46:49], v[162:165], v[170:173], v[46:49]
	v_mfma_f32_16x16x32_bf16 v[34:37], v[154:157], v[178:181], v[34:37]
	v_mfma_f32_16x16x32_bf16 v[30:33], v[162:165], v[178:181], v[30:33]
	v_mfma_f32_16x16x32_bf16 v[22:25], v[154:157], v[186:189], v[22:25]
	v_mfma_f32_16x16x32_bf16 v[14:17], v[162:165], v[186:189], v[14:17]
	v_mfma_f32_16x16x32_bf16 v[6:9], v[154:157], v[194:197], v[6:9]
	v_mfma_f32_16x16x32_bf16 v[2:5], v[162:165], v[194:197], v[2:5]
	v_mfma_f32_16x16x32_bf16 v[50:53], v[158:161], v[174:177], v[50:53]
	v_mfma_f32_16x16x32_bf16 v[46:49], v[166:169], v[174:177], v[46:49]
	v_mfma_f32_16x16x32_bf16 v[34:37], v[158:161], v[182:185], v[34:37]
	v_mfma_f32_16x16x32_bf16 v[30:33], v[166:169], v[182:185], v[30:33]
	v_mfma_f32_16x16x32_bf16 v[22:25], v[158:161], v[190:193], v[22:25]
	v_mfma_f32_16x16x32_bf16 v[14:17], v[166:169], v[190:193], v[14:17]
	v_mfma_f32_16x16x32_bf16 v[6:9], v[158:161], v[198:201], v[6:9]
	v_mfma_f32_16x16x32_bf16 v[2:5], v[166:169], v[198:201], v[2:5]
	s_barrier
	s_setprio 0
	v_add_u32_e32 v150, 0x18000, v136
	v_add_u32_e32 v166, 0x1c000, v136
	ds_read_b128 v[138:141], v150
	ds_read_b128 v[142:145], v150 offset:1024
	ds_read_b128 v[146:149], v150 offset:2048
	ds_read_b128 v[150:153], v150 offset:3072
	ds_read_b128 v[154:157], v166
	ds_read_b128 v[158:161], v166 offset:1024
	ds_read_b128 v[162:165], v166 offset:2048
	ds_read_b128 v[166:169], v166 offset:3072
	s_add_i32 s57, s58, 0xb0000
	s_mov_b32 m0, s38
	s_nop 0
	buffer_load_dwordx4 v134, s[16:19], s57 offen lds
	s_nop 0
	s_mov_b32 m0, s39
	s_nop 0
	buffer_load_dwordx4 v135, s[16:19], s57 offen lds
	ds_read_b128 v[170:173], v137 offset:32768
	ds_read_b128 v[174:177], v137 offset:33792
	ds_read_b128 v[178:181], v137 offset:34816
	ds_read_b128 v[182:185], v137 offset:35840
	ds_read_b128 v[186:189], v137 offset:36864
	ds_read_b128 v[190:193], v137 offset:37888
	ds_read_b128 v[194:197], v137 offset:38912
	ds_read_b128 v[198:201], v137 offset:39936
	s_waitcnt vmcnt(8)
	s_waitcnt lgkmcnt(0)
	s_setprio 1
	s_barrier
	v_mfma_f32_16x16x32_bf16 v[126:129], v[138:141], v[170:173], v[126:129]
	v_mfma_f32_16x16x32_bf16 v[122:125], v[146:149], v[170:173], v[122:125]
	v_mfma_f32_16x16x32_bf16 v[118:121], v[138:141], v[178:181], v[118:121]
	v_mfma_f32_16x16x32_bf16 v[106:109], v[146:149], v[178:181], v[106:109]
	v_mfma_f32_16x16x32_bf16 v[102:105], v[138:141], v[186:189], v[102:105]
	v_mfma_f32_16x16x32_bf16 v[90:93], v[146:149], v[186:189], v[90:93]
	v_mfma_f32_16x16x32_bf16 v[86:89], v[138:141], v[194:197], v[86:89]
	v_mfma_f32_16x16x32_bf16 v[74:77], v[146:149], v[194:197], v[74:77]
	v_mfma_f32_16x16x32_bf16 v[126:129], v[142:145], v[174:177], v[126:129]
	v_mfma_f32_16x16x32_bf16 v[122:125], v[150:153], v[174:177], v[122:125]
	v_mfma_f32_16x16x32_bf16 v[118:121], v[142:145], v[182:185], v[118:121]
	v_mfma_f32_16x16x32_bf16 v[106:109], v[150:153], v[182:185], v[106:109]
	v_mfma_f32_16x16x32_bf16 v[102:105], v[142:145], v[190:193], v[102:105]
	v_mfma_f32_16x16x32_bf16 v[90:93], v[150:153], v[190:193], v[90:93]
	v_mfma_f32_16x16x32_bf16 v[86:89], v[142:145], v[198:201], v[86:89]
	v_mfma_f32_16x16x32_bf16 v[74:77], v[150:153], v[198:201], v[74:77]
	v_mfma_f32_16x16x32_bf16 v[114:117], v[154:157], v[170:173], v[114:117]
	v_mfma_f32_16x16x32_bf16 v[110:113], v[162:165], v[170:173], v[110:113]
	v_mfma_f32_16x16x32_bf16 v[98:101], v[154:157], v[178:181], v[98:101]
	v_mfma_f32_16x16x32_bf16 v[94:97], v[162:165], v[178:181], v[94:97]
	v_mfma_f32_16x16x32_bf16 v[82:85], v[154:157], v[186:189], v[82:85]
	v_mfma_f32_16x16x32_bf16 v[78:81], v[162:165], v[186:189], v[78:81]
	v_mfma_f32_16x16x32_bf16 v[70:73], v[154:157], v[194:197], v[70:73]
	v_mfma_f32_16x16x32_bf16 v[66:69], v[162:165], v[194:197], v[66:69]
	v_mfma_f32_16x16x32_bf16 v[114:117], v[158:161], v[174:177], v[114:117]
	v_mfma_f32_16x16x32_bf16 v[110:113], v[166:169], v[174:177], v[110:113]
	v_mfma_f32_16x16x32_bf16 v[98:101], v[158:161], v[182:185], v[98:101]
	v_mfma_f32_16x16x32_bf16 v[94:97], v[166:169], v[182:185], v[94:97]
	v_mfma_f32_16x16x32_bf16 v[82:85], v[158:161], v[190:193], v[82:85]
	v_mfma_f32_16x16x32_bf16 v[78:81], v[166:169], v[190:193], v[78:81]
	v_mfma_f32_16x16x32_bf16 v[70:73], v[158:161], v[198:201], v[70:73]
	v_mfma_f32_16x16x32_bf16 v[66:69], v[166:169], v[198:201], v[66:69]
	s_barrier
	s_setprio 0
	ds_read_b128 v[170:173], v137 offset:49152
	ds_read_b128 v[174:177], v137 offset:50176
	s_add_i32 s57, s56, 0x80
	s_mov_b32 m0, s40
	s_nop 0
	buffer_load_dwordx4 v134, s[12:15], s57 offen lds
	ds_read_b128 v[178:181], v137 offset:51200
	ds_read_b128 v[182:185], v137 offset:52224
	s_add_i32 s56, s56, 0xb0080
	s_mov_b32 m0, s41
	s_nop 0
	buffer_load_dwordx4 v135, s[12:15], s57 offen lds
	ds_read_b128 v[186:189], v137 offset:53248
	ds_read_b128 v[190:193], v137 offset:54272
	s_nop 0
	s_mov_b32 m0, s44
	s_nop 0
	buffer_load_dwordx4 v134, s[12:15], s56 offen lds
	ds_read_b128 v[194:197], v137 offset:55296
	ds_read_b128 v[198:201], v137 offset:56320
	s_nop 0
	s_mov_b32 m0, s45
	s_nop 0
	buffer_load_dwordx4 v135, s[12:15], s56 offen lds
	s_nop 0
	s_mov_b32 m0, s42
	s_nop 0
	buffer_load_dwordx4 v134, s[16:19], s55 offen lds
	s_nop 0
	s_mov_b32 m0, s43
	s_nop 0
	buffer_load_dwordx4 v135, s[16:19], s55 offen lds
	s_waitcnt vmcnt(8)
	s_waitcnt lgkmcnt(0)
	s_setprio 1
	s_barrier
	v_mfma_f32_16x16x32_bf16 v[62:65], v[138:141], v[170:173], v[62:65]
	v_mfma_f32_16x16x32_bf16 v[58:61], v[146:149], v[170:173], v[58:61]
	v_mfma_f32_16x16x32_bf16 v[54:57], v[138:141], v[178:181], v[54:57]
	v_mfma_f32_16x16x32_bf16 v[42:45], v[146:149], v[178:181], v[42:45]
	v_mfma_f32_16x16x32_bf16 v[38:41], v[138:141], v[186:189], v[38:41]
	v_mfma_f32_16x16x32_bf16 v[26:29], v[146:149], v[186:189], v[26:29]
	v_mfma_f32_16x16x32_bf16 v[18:21], v[138:141], v[194:197], v[18:21]
	v_mfma_f32_16x16x32_bf16 v[10:13], v[146:149], v[194:197], v[10:13]
	v_mfma_f32_16x16x32_bf16 v[62:65], v[142:145], v[174:177], v[62:65]
	v_mfma_f32_16x16x32_bf16 v[58:61], v[150:153], v[174:177], v[58:61]
	v_mfma_f32_16x16x32_bf16 v[54:57], v[142:145], v[182:185], v[54:57]
	v_mfma_f32_16x16x32_bf16 v[42:45], v[150:153], v[182:185], v[42:45]
	v_mfma_f32_16x16x32_bf16 v[38:41], v[142:145], v[190:193], v[38:41]
	v_mfma_f32_16x16x32_bf16 v[26:29], v[150:153], v[190:193], v[26:29]
	v_mfma_f32_16x16x32_bf16 v[18:21], v[142:145], v[198:201], v[18:21]
	v_mfma_f32_16x16x32_bf16 v[10:13], v[150:153], v[198:201], v[10:13]
	v_mfma_f32_16x16x32_bf16 v[50:53], v[154:157], v[170:173], v[50:53]
	v_mfma_f32_16x16x32_bf16 v[46:49], v[162:165], v[170:173], v[46:49]
	v_mfma_f32_16x16x32_bf16 v[34:37], v[154:157], v[178:181], v[34:37]
	v_mfma_f32_16x16x32_bf16 v[30:33], v[162:165], v[178:181], v[30:33]
	v_mfma_f32_16x16x32_bf16 v[22:25], v[154:157], v[186:189], v[22:25]
	v_mfma_f32_16x16x32_bf16 v[14:17], v[162:165], v[186:189], v[14:17]
	v_mfma_f32_16x16x32_bf16 v[6:9], v[154:157], v[194:197], v[6:9]
	v_mfma_f32_16x16x32_bf16 v[2:5], v[162:165], v[194:197], v[2:5]
	v_mfma_f32_16x16x32_bf16 v[50:53], v[158:161], v[174:177], v[50:53]
	v_mfma_f32_16x16x32_bf16 v[46:49], v[166:169], v[174:177], v[46:49]
	v_mfma_f32_16x16x32_bf16 v[34:37], v[158:161], v[182:185], v[34:37]
	v_mfma_f32_16x16x32_bf16 v[30:33], v[166:169], v[182:185], v[30:33]
	v_mfma_f32_16x16x32_bf16 v[22:25], v[158:161], v[190:193], v[22:25]
	v_mfma_f32_16x16x32_bf16 v[14:17], v[166:169], v[190:193], v[14:17]
	v_mfma_f32_16x16x32_bf16 v[6:9], v[158:161], v[198:201], v[6:9]
	v_mfma_f32_16x16x32_bf16 v[2:5], v[166:169], v[198:201], v[2:5]
	s_barrier
	s_setprio 0
	s_add_i32 s2, s2, 2
	s_addk_i32 s3, 0x100
	s_cmp_gt_u32 s2, 41
	s_cbranch_scc0 .LBB0_1135
	s_andn2_b64 vcc, exec, s[4:5]
	s_cbranch_vccnz .LBB0_1123
	v_mov_b32_e32 v2, 0
	s_mov_b32 s20, s50
	s_mov_b32 s25, s51
	s_mov_b32 s30, s54
	s_mov_b32 s36, s53
	s_mov_b32 s49, s52
	v_mov_b32_e32 v3, v2
	v_mov_b32_e32 v4, v2
	v_mov_b32_e32 v5, v2
	v_mov_b32_e32 v6, v2
	v_mov_b32_e32 v7, v2
	v_mov_b32_e32 v8, v2
	v_mov_b32_e32 v9, v2
	v_mov_b32_e32 v14, v2
	v_mov_b32_e32 v15, v2
	v_mov_b32_e32 v16, v2
	v_mov_b32_e32 v17, v2
	v_mov_b32_e32 v22, v2
	v_mov_b32_e32 v23, v2
	v_mov_b32_e32 v24, v2
	v_mov_b32_e32 v25, v2
	v_mov_b32_e32 v30, v2
	v_mov_b32_e32 v31, v2
	v_mov_b32_e32 v32, v2
	v_mov_b32_e32 v33, v2
	v_mov_b32_e32 v34, v2
	v_mov_b32_e32 v35, v2
	v_mov_b32_e32 v36, v2
	v_mov_b32_e32 v37, v2
	v_mov_b32_e32 v46, v2
	v_mov_b32_e32 v47, v2
	v_mov_b32_e32 v48, v2
	v_mov_b32_e32 v49, v2
	v_mov_b32_e32 v50, v2
	v_mov_b32_e32 v51, v2
	v_mov_b32_e32 v52, v2
	v_mov_b32_e32 v53, v2
	v_mov_b32_e32 v10, v2
	v_mov_b32_e32 v11, v2
	v_mov_b32_e32 v12, v2
	v_mov_b32_e32 v13, v2
	v_mov_b32_e32 v18, v2
	v_mov_b32_e32 v19, v2
	v_mov_b32_e32 v20, v2
	v_mov_b32_e32 v21, v2
	v_mov_b32_e32 v26, v2
	v_mov_b32_e32 v27, v2
	v_mov_b32_e32 v28, v2
	v_mov_b32_e32 v29, v2
	v_mov_b32_e32 v38, v2
	v_mov_b32_e32 v39, v2
	v_mov_b32_e32 v40, v2
	v_mov_b32_e32 v41, v2
	v_mov_b32_e32 v42, v2
	v_mov_b32_e32 v43, v2
	v_mov_b32_e32 v44, v2
	v_mov_b32_e32 v45, v2
	v_mov_b32_e32 v54, v2
	v_mov_b32_e32 v55, v2
	v_mov_b32_e32 v56, v2
	v_mov_b32_e32 v57, v2
	v_mov_b32_e32 v58, v2
	v_mov_b32_e32 v59, v2
	v_mov_b32_e32 v60, v2
	v_mov_b32_e32 v61, v2
	v_mov_b32_e32 v62, v2
	v_mov_b32_e32 v63, v2
	v_mov_b32_e32 v64, v2
	v_mov_b32_e32 v65, v2
	v_mov_b32_e32 v66, v2
	v_mov_b32_e32 v67, v2
	v_mov_b32_e32 v68, v2
	v_mov_b32_e32 v69, v2
	v_mov_b32_e32 v70, v2
	v_mov_b32_e32 v71, v2
	v_mov_b32_e32 v72, v2
	v_mov_b32_e32 v73, v2
	v_mov_b32_e32 v78, v2
	v_mov_b32_e32 v79, v2
	v_mov_b32_e32 v80, v2
	v_mov_b32_e32 v81, v2
	v_mov_b32_e32 v82, v2
	v_mov_b32_e32 v83, v2
	v_mov_b32_e32 v84, v2
	v_mov_b32_e32 v85, v2
	v_mov_b32_e32 v94, v2
	v_mov_b32_e32 v95, v2
	v_mov_b32_e32 v96, v2
	v_mov_b32_e32 v97, v2
	v_mov_b32_e32 v98, v2
	v_mov_b32_e32 v99, v2
	v_mov_b32_e32 v100, v2
	v_mov_b32_e32 v101, v2
	v_mov_b32_e32 v110, v2
	v_mov_b32_e32 v111, v2
	v_mov_b32_e32 v112, v2
	v_mov_b32_e32 v113, v2
	v_mov_b32_e32 v114, v2
	v_mov_b32_e32 v115, v2
	v_mov_b32_e32 v116, v2
	v_mov_b32_e32 v117, v2
	v_mov_b32_e32 v74, v2
	v_mov_b32_e32 v75, v2
	v_mov_b32_e32 v76, v2
	v_mov_b32_e32 v77, v2
	v_mov_b32_e32 v86, v2
	v_mov_b32_e32 v87, v2
	v_mov_b32_e32 v88, v2
	v_mov_b32_e32 v89, v2
	v_mov_b32_e32 v90, v2
	v_mov_b32_e32 v91, v2
	v_mov_b32_e32 v92, v2
	v_mov_b32_e32 v93, v2
	v_mov_b32_e32 v102, v2
	v_mov_b32_e32 v103, v2
	v_mov_b32_e32 v104, v2
	v_mov_b32_e32 v105, v2
	v_mov_b32_e32 v106, v2
	v_mov_b32_e32 v107, v2
	v_mov_b32_e32 v108, v2
	v_mov_b32_e32 v109, v2
	v_mov_b32_e32 v118, v2
	v_mov_b32_e32 v119, v2
	v_mov_b32_e32 v120, v2
	v_mov_b32_e32 v121, v2
	v_mov_b32_e32 v122, v2
	v_mov_b32_e32 v123, v2
	v_mov_b32_e32 v124, v2
	v_mov_b32_e32 v125, v2
	v_mov_b32_e32 v126, v2
	v_mov_b32_e32 v127, v2
	v_mov_b32_e32 v128, v2
	v_mov_b32_e32 v129, v2
	s_branch .LBB0_1123
